# attention: DMA issue for tile s+3 moved between the ds_reads and their wait (overlaps LDS latency)
# speedup vs baseline: 1.0056x; 1.0004x over previous
; __device__ __forceinline__ void phase_attn(KP kp, int l, unsigned char* shm) {
;     ...
;     int r = q;
;     if (gridDim.x == 256 && q < MP) r = ((q >> 3) & 7) * 4096 + (q >> 11) * 256 + ((q >> 6) & 31) * 8 + (q & 7);
;     const bf16_t *kbase, *vbase;
;     int n;
;     if (r < MP) {
;       const int b = r >> 12, t = r & 4095;
;       kbase = (const bf16_t*)(ws + W_KP) + (size_t)b * 4096 * 128;
;       vbase = (const bf16_t*)(ws + W_VP) + (size_t)b * 4096 * 128;
;       n = ((t >> 6) + 1) * 64;
;     } else {
;       const int sb = (r - MP) >> 5;
;       kbase = (const bf16_t*)(ws + W_KS) + (size_t)(l * 16 + sb) * 2080 * 128;
;       vbase = (const bf16_t*)(ws + W_VS) + (size_t)(l * 16 + sb) * 2080 * 128;
;       n = 2080;
;     }
;     const int cnt = n < 256 ? n : 256;
;     {
;       u32x2 sv = *(const u32x2*)(SEL + (size_t)r * 256 + lane * 4);
;       const int k0 = lane * 4;
;       unsigned a0 = sv[0] & 0xffffu, a1 = sv[0] >> 16, a2 = sv[1] & 0xffffu, a3 = sv[1] >> 16;
;       a0 = (k0 < cnt) ? a0 : 0u; a1 = (k0 + 1 < cnt) ? a1 : 0u; a2 = (k0 + 2 < cnt) ? a2 : 0u; a3 = (k0 + 3 < cnt) ? a3 : 0u;
;       u32x2 o;
;       o[0] = a0 | (a1 << 16); o[1] = a2 | (a3 << 16);
;       *(u32x2*)(selw + lane * 4) = o;
;     }
;     __builtin_amdgcn_wave_barrier();
;     bf16x8 kpre[8][2];
; #pragma unroll
;     for (int kvh = 0; kvh < 2; ++kvh) {
;       bf16x8 bq0, bq1;
; #pragma unroll
;       for (int e = 0; e < 8; ++e) { bq0[e] = 0; bq1[e] = 0; }
;       if (nn < 4) {
;         const bf16_t* qp = Q + (size_t)r * 512 + (kvh * 4 + nn) * 64 + kg * 8;
;         bq0 = *(const bf16x8*)qp;
;         bq1 = *(const bf16x8*)(qp + 32);
;       }
;       f32x4 lg[16];
;       for (int repQ = 0; repQ < ((PROBE & 128) ? 2 : 1); ++repQ)
;       {
; #pragma unroll
;         for (int hb = 0; hb < 2; ++hb) {
;           bf16x8 ka[8][2];
;           if (kvh == 1 && hb == 0) {
; #pragma unroll
;             for (int k8 = 0; k8 < 8; ++k8) { ka[k8][0] = kpre[k8][0]; ka[k8][1] = kpre[k8][1]; }
;           } else {
; #pragma unroll
;             for (int k8 = 0; k8 < 8; ++k8) {
;               const int idx = selw[(hb * 8 + k8) * 16 + nn];
;               const bf16_t* kp = kbase + (size_t)idx * 128 + kvh * 64 + kg * 8;
;               ka[k8][0] = *(const bf16x8*)kp;
;               ka[k8][1] = *(const bf16x8*)(kp + 32);
;             }
;           }
.Lattn_join_3:
	s_add_u32 s28, s0, s7
	s_addc_u32 s29, s1, 0
	s_add_u32 s30, s0, s8
	s_addc_u32 s31, s1, 0
	s_lshl_b32 s6, s51, 9
	s_add_u32 s6, s6, 0x1b3c2000
	s_add_u32 s38, s0, s6
	s_addc_u32 s39, s1, 0
	s_lshl_b32 s6, s51, 10
	s_add_u32 s7, s6, 0x7ac0000
	s_add_u32 s40, s0, s7
	s_addc_u32 s41, s1, 0
	s_add_u32 s7, s6, 0x1c402000
	s_add_u32 s36, s0, s7
	s_addc_u32 s37, s1, 0
	global_load_dwordx2 v[198:199], v188, s[38:39]
	s_mov_b64 exec, s[42:43]
	global_load_dwordx4 v[144:147], v189, s[40:41]
	global_load_dwordx4 v[148:151], v189, s[40:41] offset:64
	global_load_dwordx4 v[152:155], v189, s[40:41] offset:512
	global_load_dwordx4 v[156:159], v189, s[40:41] offset:576
	s_mov_b64 exec, -1
	s_waitcnt vmcnt(0)
	s_lshr_b32 s6, s45, 2
	v_cmp_gt_u32_e32 vcc, s6, v252
	s_nop 1
	v_cndmask_b32_e32 v198, 0, v198, vcc
	v_cndmask_b32_e32 v199, 0, v199, vcc
	ds_write_b64 v186, v[198:199]
	ds_read_u16 v0, v187 offset:0
	ds_read_u16 v1, v187 offset:16
	ds_read_u16 v2, v187 offset:32
	ds_read_u16 v3, v187 offset:48
	ds_read_u16 v4, v187 offset:64
	ds_read_u16 v5, v187 offset:80
	ds_read_u16 v6, v187 offset:96
	ds_read_u16 v7, v187 offset:112
	s_waitcnt lgkmcnt(0)
	v_lshl_add_u32 v0, v0, 8, v193
	v_lshl_add_u32 v1, v1, 8, v194
	v_lshl_add_u32 v2, v2, 8, v195
	v_lshl_add_u32 v3, v3, 8, v196
	v_lshl_add_u32 v4, v4, 8, v193
	v_lshl_add_u32 v5, v5, 8, v194
	v_lshl_add_u32 v6, v6, 8, v195
	v_lshl_add_u32 v7, v7, 8, v196
	ds_read_u16 v8, v187 offset:128
	ds_read_u16 v9, v187 offset:144
	ds_read_u16 v10, v187 offset:160
	ds_read_u16 v11, v187 offset:176
	ds_read_u16 v12, v187 offset:192
	ds_read_u16 v13, v187 offset:208
	ds_read_u16 v14, v187 offset:224
	ds_read_u16 v15, v187 offset:240
	s_waitcnt lgkmcnt(0)
	v_lshl_add_u32 v8, v8, 8, v193
	v_lshl_add_u32 v9, v9, 8, v194
	v_lshl_add_u32 v10, v10, 8, v195
	v_lshl_add_u32 v11, v11, 8, v196
	v_lshl_add_u32 v12, v12, 8, v193
	v_lshl_add_u32 v13, v13, 8, v194
	v_lshl_add_u32 v14, v14, 8, v195
	v_lshl_add_u32 v15, v15, 8, v196
	ds_read_u16 v16, v187 offset:256
	ds_read_u16 v18, v187 offset:272
	ds_read_u16 v19, v187 offset:288
	ds_read_u16 v20, v187 offset:304
	ds_read_u16 v21, v187 offset:320
	ds_read_u16 v22, v187 offset:336
	ds_read_u16 v23, v187 offset:352
	ds_read_u16 v24, v187 offset:368
	s_waitcnt lgkmcnt(0)
	v_lshl_add_u32 v16, v16, 8, v193
	v_lshl_add_u32 v18, v18, 8, v194
	v_lshl_add_u32 v19, v19, 8, v195
	v_lshl_add_u32 v20, v20, 8, v196
	v_lshl_add_u32 v21, v21, 8, v193
	v_lshl_add_u32 v22, v22, 8, v194
	v_lshl_add_u32 v23, v23, 8, v195
	v_lshl_add_u32 v24, v24, 8, v196
	ds_read_u16 v25, v187 offset:384
	ds_read_u16 v26, v187 offset:400
	ds_read_u16 v27, v187 offset:416
	ds_read_u16 v28, v187 offset:432
	ds_read_u16 v29, v187 offset:448
	ds_read_u16 v30, v187 offset:464
	ds_read_u16 v31, v187 offset:480
	ds_read_u16 v219, v187 offset:496
	s_waitcnt lgkmcnt(0)
	v_lshl_add_u32 v25, v25, 8, v193
	v_lshl_add_u32 v26, v26, 8, v194
	v_lshl_add_u32 v27, v27, 8, v195
	v_lshl_add_u32 v28, v28, 8, v196
	v_lshl_add_u32 v29, v29, 8, v193
	v_lshl_add_u32 v30, v30, 8, v194
	v_lshl_add_u32 v31, v31, 8, v195
	v_lshl_add_u32 v219, v219, 8, v196
	s_mov_b32 m0, s46
	s_nop 0
	global_load_lds_dwordx4 v0, s[28:29]
	global_load_lds_dwordx4 v1, s[28:29] offset:1024
	global_load_lds_dwordx4 v2, s[28:29] offset:2048
	global_load_lds_dwordx4 v3, s[28:29] offset:3072
	s_mov_b32 m0, s47
	s_nop 0
	global_load_lds_dwordx4 v4, s[28:29]
	global_load_lds_dwordx4 v5, s[28:29] offset:1024
	global_load_lds_dwordx4 v6, s[28:29] offset:2048
	global_load_lds_dwordx4 v7, s[28:29] offset:3072
	s_mov_b32 m0, s48
	s_nop 0
	global_load_lds_dwordx4 v8, s[28:29]
	global_load_lds_dwordx4 v9, s[28:29] offset:1024
	global_load_lds_dwordx4 v10, s[28:29] offset:2048
	global_load_lds_dwordx4 v11, s[28:29] offset:3072
	global_load_dword v209, v17, s[0:1]
	global_load_dword v209, v17, s[0:1]
	global_load_dword v209, v17, s[0:1]
	global_load_dword v209, v17, s[0:1]
	s_mov_b64 s[20:21], s[28:29]
	s_mov_b64 s[22:23], s[30:31]
	s_add_u32 s24, s28, 0x80
	s_addc_u32 s25, s29, 0
	s_add_u32 s26, s30, 0x80
	s_addc_u32 s27, s31, 0
	s_mov_b64 s[34:35], s[36:37]
	s_mov_b32 s44, s45
; __device__ __forceinline__ void phase_attn(KP kp, int l, unsigned char* shm) {
;     ...
;         for (int hb = 0; hb < 2; ++hb) {
;           bf16x8 ka[8][2];
;           if (kvh == 1 && hb == 0) {
; #pragma unroll
;             for (int k8 = 0; k8 < 8; ++k8) { ka[k8][0] = kpre[k8][0]; ka[k8][1] = kpre[k8][1]; }
;           } else {
; #pragma unroll
;             for (int k8 = 0; k8 < 8; ++k8) {
;               const int idx = selw[(hb * 8 + k8) * 16 + nn];
;               const bf16_t* kp = kbase + (size_t)idx * 128 + kvh * 64 + kg * 8;
;               ka[k8][0] = *(const bf16x8*)kp;
;               ka[k8][1] = *(const bf16x8*)(kp + 32);
;             }
;           }
;           __builtin_amdgcn_sched_barrier(0);
; #pragma unroll
;           for (int k8 = 0; k8 < 8; ++k8) {
;             f32x4 a = (f32x4){0.f, 0.f, 0.f, 0.f};
;             a = __builtin_amdgcn_mfma_f32_16x16x32_bf16(ka[k8][0], bq0, a, 0, 0, 0);
;             a = __builtin_amdgcn_mfma_f32_16x16x32_bf16(ka[k8][1], bq1, a, 0, 0, 0);
;             lg[hb * 8 + k8] = a;
;           }
;           __builtin_amdgcn_sched_barrier(0);
;         }
;       }
;       u32x4 vr[32];
; #pragma unroll
;       for (int i = 0; i < 16; ++i) {
;         const int idx = selw[i * 8 + ks8];
;         vr[i] = *(const u32x4*)(vbase + (size_t)idx * 128 + kvh * 64 + dc * 8);
;       }
;       float mx = -1e30f;
; #pragma unroll
;       for (int kb = 0; kb < 16; ++kb)
; #pragma unroll
;         for (int j = 0; j < 4; ++j) {
;           const int key = kb * 16 + kg * 4 + j;
;           lg[kb][j] = key < cnt ? lg[kb][j] : -1e30f;
;           mx = fmaxf(mx, lg[kb][j]);
;         }
.Lattn_loop:
	s_waitcnt vmcnt(12)
	ds_read_b128 v[160:163], v180 offset:0
	ds_read_b128 v[164:167], v181 offset:0
	ds_read_b128 v[168:171], v180 offset:2048
	ds_read_b128 v[172:175], v181 offset:2048
	s_mov_b32 m0, s49
	s_nop 0
	global_load_lds_dwordx4 v12, s[20:21]
	global_load_lds_dwordx4 v13, s[20:21] offset:1024
	global_load_lds_dwordx4 v14, s[20:21] offset:2048
	global_load_lds_dwordx4 v15, s[20:21] offset:3072
	s_waitcnt lgkmcnt(0)
	v_mfma_f32_16x16x32_bf16 v[32:35], v[160:163], v[144:147], 0
	v_mfma_f32_16x16x32_bf16 v[36:39], v[168:171], v[144:147], 0
	v_mfma_f32_16x16x32_bf16 v[32:35], v[164:167], v[148:151], v[32:35]
	v_mfma_f32_16x16x32_bf16 v[36:39], v[172:175], v[148:151], v[36:39]
	s_waitcnt vmcnt(12)
	ds_read_b128 v[160:163], v180 offset:4096
	ds_read_b128 v[164:167], v181 offset:4096
	ds_read_b128 v[168:171], v180 offset:6144
	ds_read_b128 v[172:175], v181 offset:6144
	s_mov_b32 m0, s46
	s_nop 0
	global_load_lds_dwordx4 v16, s[20:21]
	global_load_lds_dwordx4 v18, s[20:21] offset:1024
	global_load_lds_dwordx4 v19, s[20:21] offset:2048
	global_load_lds_dwordx4 v20, s[20:21] offset:3072
	s_waitcnt lgkmcnt(0)
	v_mfma_f32_16x16x32_bf16 v[40:43], v[160:163], v[144:147], 0
	v_mfma_f32_16x16x32_bf16 v[44:47], v[168:171], v[144:147], 0
	v_mfma_f32_16x16x32_bf16 v[40:43], v[164:167], v[148:151], v[40:43]
	v_mfma_f32_16x16x32_bf16 v[44:47], v[172:175], v[148:151], v[44:47]
	s_waitcnt vmcnt(12)
	ds_read_b128 v[160:163], v180 offset:8192
	ds_read_b128 v[164:167], v181 offset:8192
	ds_read_b128 v[168:171], v180 offset:10240
	ds_read_b128 v[172:175], v181 offset:10240
	s_mov_b32 m0, s47
	s_nop 0
	global_load_lds_dwordx4 v21, s[20:21]
	global_load_lds_dwordx4 v22, s[20:21] offset:1024
	global_load_lds_dwordx4 v23, s[20:21] offset:2048
	global_load_lds_dwordx4 v24, s[20:21] offset:3072
	s_waitcnt lgkmcnt(0)
	v_mfma_f32_16x16x32_bf16 v[48:51], v[160:163], v[144:147], 0
	v_mfma_f32_16x16x32_bf16 v[52:55], v[168:171], v[144:147], 0
	v_mfma_f32_16x16x32_bf16 v[48:51], v[164:167], v[148:151], v[48:51]
	v_mfma_f32_16x16x32_bf16 v[52:55], v[172:175], v[148:151], v[52:55]
	s_waitcnt vmcnt(8)
	ds_read_b128 v[160:163], v180 offset:12288
	ds_read_b128 v[164:167], v181 offset:12288
	ds_read_b128 v[168:171], v180 offset:14336
	ds_read_b128 v[172:175], v181 offset:14336
	s_mov_b32 m0, s48
	s_nop 0
	global_load_lds_dwordx4 v25, s[20:21]
	global_load_lds_dwordx4 v26, s[20:21] offset:1024
	global_load_lds_dwordx4 v27, s[20:21] offset:2048
	global_load_lds_dwordx4 v28, s[20:21] offset:3072
	s_waitcnt lgkmcnt(0)
	v_mfma_f32_16x16x32_bf16 v[56:59], v[160:163], v[144:147], 0
	v_mfma_f32_16x16x32_bf16 v[60:63], v[168:171], v[144:147], 0
	v_mfma_f32_16x16x32_bf16 v[56:59], v[164:167], v[148:151], v[56:59]
	v_mfma_f32_16x16x32_bf16 v[60:63], v[172:175], v[148:151], v[60:63]
	s_waitcnt vmcnt(8)
	ds_read_b128 v[160:163], v180 offset:0
	ds_read_b128 v[164:167], v181 offset:0
	ds_read_b128 v[168:171], v180 offset:2048
	ds_read_b128 v[172:175], v181 offset:2048
	s_mov_b32 m0, s49
	s_nop 0
	global_load_lds_dwordx4 v29, s[20:21]
	global_load_lds_dwordx4 v30, s[20:21] offset:1024
	global_load_lds_dwordx4 v31, s[20:21] offset:2048
	global_load_lds_dwordx4 v219, s[20:21] offset:3072
	s_waitcnt lgkmcnt(0)
	v_mfma_f32_16x16x32_bf16 v[64:67], v[160:163], v[144:147], 0
	v_mfma_f32_16x16x32_bf16 v[68:71], v[168:171], v[144:147], 0
	v_mfma_f32_16x16x32_bf16 v[64:67], v[164:167], v[148:151], v[64:67]
	v_mfma_f32_16x16x32_bf16 v[68:71], v[172:175], v[148:151], v[68:71]
	s_waitcnt vmcnt(8)
	ds_read_b128 v[160:163], v180 offset:4096
	ds_read_b128 v[164:167], v181 offset:4096
	ds_read_b128 v[168:171], v180 offset:6144
	ds_read_b128 v[172:175], v181 offset:6144
	s_mov_b32 m0, s46
	s_nop 0
	global_load_lds_dwordx4 v0, s[22:23]
	global_load_lds_dwordx4 v1, s[22:23] offset:1024
	global_load_lds_dwordx4 v2, s[22:23] offset:2048
	global_load_lds_dwordx4 v3, s[22:23] offset:3072
	s_waitcnt lgkmcnt(0)
	v_mfma_f32_16x16x32_bf16 v[72:75], v[160:163], v[144:147], 0
	v_mfma_f32_16x16x32_bf16 v[76:79], v[168:171], v[144:147], 0
	v_mfma_f32_16x16x32_bf16 v[72:75], v[164:167], v[148:151], v[72:75]
	v_mfma_f32_16x16x32_bf16 v[76:79], v[172:175], v[148:151], v[76:79]
	s_waitcnt vmcnt(8)
	ds_read_b128 v[160:163], v180 offset:8192
	ds_read_b128 v[164:167], v181 offset:8192
	ds_read_b128 v[168:171], v180 offset:10240
	ds_read_b128 v[172:175], v181 offset:10240
	s_mov_b32 m0, s47
	s_nop 0
	global_load_lds_dwordx4 v4, s[22:23]
	global_load_lds_dwordx4 v5, s[22:23] offset:1024
	global_load_lds_dwordx4 v6, s[22:23] offset:2048
	global_load_lds_dwordx4 v7, s[22:23] offset:3072
	s_waitcnt lgkmcnt(0)
	v_mfma_f32_16x16x32_bf16 v[80:83], v[160:163], v[144:147], 0
	v_mfma_f32_16x16x32_bf16 v[84:87], v[168:171], v[144:147], 0
	v_mfma_f32_16x16x32_bf16 v[80:83], v[164:167], v[148:151], v[80:83]
	v_mfma_f32_16x16x32_bf16 v[84:87], v[172:175], v[148:151], v[84:87]
	s_waitcnt vmcnt(8)
	ds_read_b128 v[160:163], v180 offset:12288
	ds_read_b128 v[164:167], v181 offset:12288
	ds_read_b128 v[168:171], v180 offset:14336
	ds_read_b128 v[172:175], v181 offset:14336
	s_mov_b32 m0, s48
	s_nop 0
	global_load_lds_dwordx4 v8, s[22:23]
	global_load_lds_dwordx4 v9, s[22:23] offset:1024
	global_load_lds_dwordx4 v10, s[22:23] offset:2048
	global_load_lds_dwordx4 v11, s[22:23] offset:3072
	s_waitcnt lgkmcnt(0)
	v_mfma_f32_16x16x32_bf16 v[88:91], v[160:163], v[144:147], 0
	v_mfma_f32_16x16x32_bf16 v[92:95], v[168:171], v[144:147], 0
	v_mfma_f32_16x16x32_bf16 v[88:91], v[164:167], v[148:151], v[88:91]
	v_mfma_f32_16x16x32_bf16 v[92:95], v[172:175], v[148:151], v[92:95]
	s_nop 7
	s_nop 3
	s_cmp_ge_u32 s44, 0x100
	s_cbranch_scc1 .Lattn_nomask_4
	s_cmp_ge_u32 s44, 0xc0
	s_cbranch_scc1 .Lattn_m192_5
	s_cmp_ge_u32 s44, 0x80
	s_cbranch_scc1 .Lattn_m128_6
	v_mov_b32_e32 v48, 0xf149f2ca
	v_mov_b32_e32 v49, 0xf149f2ca
	v_mov_b32_e32 v50, 0xf149f2ca
	v_mov_b32_e32 v51, 0xf149f2ca
	v_mov_b32_e32 v52, 0xf149f2ca
	v_mov_b32_e32 v53, 0xf149f2ca
	v_mov_b32_e32 v54, 0xf149f2ca
	v_mov_b32_e32 v55, 0xf149f2ca
	v_mov_b32_e32 v56, 0xf149f2ca
	v_mov_b32_e32 v57, 0xf149f2ca
	v_mov_b32_e32 v58, 0xf149f2ca
	v_mov_b32_e32 v59, 0xf149f2ca
	v_mov_b32_e32 v60, 0xf149f2ca
	v_mov_b32_e32 v61, 0xf149f2ca
	v_mov_b32_e32 v62, 0xf149f2ca
	v_mov_b32_e32 v63, 0xf149f2ca

; __device__ __forceinline__ void phase_attn(KP kp, int l, unsigned char* shm) {
;     ...
;       float mx = -1e30f;
; #pragma unroll
;       for (int kb = 0; kb < 16; ++kb)
; #pragma unroll
;         for (int j = 0; j < 4; ++j) {
;           const int key = kb * 16 + kg * 4 + j;
;           lg[kb][j] = key < cnt ? lg[kb][j] : -1e30f;
;           mx = fmaxf(mx, lg[kb][j]);
;         }
;       mx = fmaxf(mx, __shfl_xor(mx, 16));
;       mx = fmaxf(mx, __shfl_xor(mx, 32));
;       float sum = 0.f;
; #pragma unroll
;       for (int kb = 0; kb < 16; ++kb)
; #pragma unroll
;         for (int j = 0; j < 4; ++j) { lg[kb][j] = __builtin_amdgcn_exp2f(lg[kb][j] - mx); sum += lg[kb][j]; }
;       sum += __shfl_xor(sum, 16);
;       sum += __shfl_xor(sum, 32);
.Lattn_nomask_4:
	v_max3_f32 v176, v32, v33, v34
	v_max3_f32 v176, v176, v35, v36
	v_max3_f32 v176, v176, v37, v38
	v_max3_f32 v176, v176, v39, v40
	v_max3_f32 v176, v176, v41, v42
	v_max3_f32 v176, v176, v43, v44
	v_max3_f32 v176, v176, v45, v46
	v_max3_f32 v176, v176, v47, v48
	v_max3_f32 v176, v176, v49, v50
	v_max3_f32 v176, v176, v51, v52
	v_max3_f32 v176, v176, v53, v54
	v_max3_f32 v176, v176, v55, v56
	v_max3_f32 v176, v176, v57, v58
	v_max3_f32 v176, v176, v59, v60
	v_max3_f32 v176, v176, v61, v62
	v_max3_f32 v176, v176, v63, v64
	v_max3_f32 v176, v176, v65, v66
	v_max3_f32 v176, v176, v67, v68
	v_max3_f32 v176, v176, v69, v70
	v_max3_f32 v176, v176, v71, v72
	v_max3_f32 v176, v176, v73, v74
	v_max3_f32 v176, v176, v75, v76
	v_max3_f32 v176, v176, v77, v78
	v_max3_f32 v176, v176, v79, v80
	v_max3_f32 v176, v176, v81, v82
	v_max3_f32 v176, v176, v83, v84
	v_max3_f32 v176, v176, v85, v86
	v_max3_f32 v176, v176, v87, v88
	v_max3_f32 v176, v176, v89, v90
	v_max3_f32 v176, v176, v91, v92
	v_max3_f32 v176, v176, v93, v94
	v_max_f32_e32 v176, v176, v95
	ds_bpermute_b32 v197, v191, v176
	s_waitcnt lgkmcnt(0)
	v_max_f32_e32 v176, v176, v197
	ds_bpermute_b32 v197, v192, v176
	s_waitcnt lgkmcnt(0)
	v_max_f32_e32 v176, v176, v197
	v_mov_b32_e32 v177, v176
	v_pk_add_f32 v[32:33], v[32:33], v[176:177] neg_lo:[0,1] neg_hi:[0,1]
	v_pk_add_f32 v[34:35], v[34:35], v[176:177] neg_lo:[0,1] neg_hi:[0,1]
	v_pk_add_f32 v[36:37], v[36:37], v[176:177] neg_lo:[0,1] neg_hi:[0,1]
	v_pk_add_f32 v[38:39], v[38:39], v[176:177] neg_lo:[0,1] neg_hi:[0,1]
	v_pk_add_f32 v[40:41], v[40:41], v[176:177] neg_lo:[0,1] neg_hi:[0,1]
	v_pk_add_f32 v[42:43], v[42:43], v[176:177] neg_lo:[0,1] neg_hi:[0,1]
	v_pk_add_f32 v[44:45], v[44:45], v[176:177] neg_lo:[0,1] neg_hi:[0,1]
	v_pk_add_f32 v[46:47], v[46:47], v[176:177] neg_lo:[0,1] neg_hi:[0,1]
	v_pk_add_f32 v[48:49], v[48:49], v[176:177] neg_lo:[0,1] neg_hi:[0,1]
	v_pk_add_f32 v[50:51], v[50:51], v[176:177] neg_lo:[0,1] neg_hi:[0,1]
	v_pk_add_f32 v[52:53], v[52:53], v[176:177] neg_lo:[0,1] neg_hi:[0,1]
	v_pk_add_f32 v[54:55], v[54:55], v[176:177] neg_lo:[0,1] neg_hi:[0,1]
	v_pk_add_f32 v[56:57], v[56:57], v[176:177] neg_lo:[0,1] neg_hi:[0,1]
	v_pk_add_f32 v[58:59], v[58:59], v[176:177] neg_lo:[0,1] neg_hi:[0,1]
	v_pk_add_f32 v[60:61], v[60:61], v[176:177] neg_lo:[0,1] neg_hi:[0,1]
	v_pk_add_f32 v[62:63], v[62:63], v[176:177] neg_lo:[0,1] neg_hi:[0,1]
	v_pk_add_f32 v[64:65], v[64:65], v[176:177] neg_lo:[0,1] neg_hi:[0,1]
	v_pk_add_f32 v[66:67], v[66:67], v[176:177] neg_lo:[0,1] neg_hi:[0,1]
	v_pk_add_f32 v[68:69], v[68:69], v[176:177] neg_lo:[0,1] neg_hi:[0,1]
	v_pk_add_f32 v[70:71], v[70:71], v[176:177] neg_lo:[0,1] neg_hi:[0,1]
	v_pk_add_f32 v[72:73], v[72:73], v[176:177] neg_lo:[0,1] neg_hi:[0,1]
	v_pk_add_f32 v[74:75], v[74:75], v[176:177] neg_lo:[0,1] neg_hi:[0,1]
	v_pk_add_f32 v[76:77], v[76:77], v[176:177] neg_lo:[0,1] neg_hi:[0,1]
	v_pk_add_f32 v[78:79], v[78:79], v[176:177] neg_lo:[0,1] neg_hi:[0,1]
	v_pk_add_f32 v[80:81], v[80:81], v[176:177] neg_lo:[0,1] neg_hi:[0,1]
	v_pk_add_f32 v[82:83], v[82:83], v[176:177] neg_lo:[0,1] neg_hi:[0,1]
	v_pk_add_f32 v[84:85], v[84:85], v[176:177] neg_lo:[0,1] neg_hi:[0,1]
	v_pk_add_f32 v[86:87], v[86:87], v[176:177] neg_lo:[0,1] neg_hi:[0,1]
	v_pk_add_f32 v[88:89], v[88:89], v[176:177] neg_lo:[0,1] neg_hi:[0,1]
	v_pk_add_f32 v[90:91], v[90:91], v[176:177] neg_lo:[0,1] neg_hi:[0,1]
	v_pk_add_f32 v[92:93], v[92:93], v[176:177] neg_lo:[0,1] neg_hi:[0,1]
	v_pk_add_f32 v[94:95], v[94:95], v[176:177] neg_lo:[0,1] neg_hi:[0,1]
	v_exp_f32_e32 v32, v32
	v_exp_f32_e32 v33, v33
	v_exp_f32_e32 v34, v34
	v_exp_f32_e32 v35, v35
	v_exp_f32_e32 v36, v36
	v_exp_f32_e32 v37, v37
	v_pk_add_f32 v[178:179], v[32:33], v[34:35]
	v_exp_f32_e32 v38, v38
	v_exp_f32_e32 v39, v39
	v_pk_add_f32 v[178:179], v[178:179], v[36:37]
	v_exp_f32_e32 v40, v40
	v_exp_f32_e32 v41, v41
	v_pk_add_f32 v[178:179], v[178:179], v[38:39]
	v_exp_f32_e32 v42, v42
	v_exp_f32_e32 v43, v43
	v_pk_add_f32 v[178:179], v[178:179], v[40:41]
	v_exp_f32_e32 v44, v44
	v_exp_f32_e32 v45, v45
	v_pk_add_f32 v[178:179], v[178:179], v[42:43]
	v_exp_f32_e32 v46, v46
	v_exp_f32_e32 v47, v47
	v_pk_add_f32 v[178:179], v[178:179], v[44:45]
	v_exp_f32_e32 v48, v48
	v_exp_f32_e32 v49, v49
	v_pk_add_f32 v[178:179], v[178:179], v[46:47]
	v_exp_f32_e32 v50, v50
	v_exp_f32_e32 v51, v51
	v_pk_add_f32 v[178:179], v[178:179], v[48:49]
	v_exp_f32_e32 v52, v52
	v_exp_f32_e32 v53, v53
	v_pk_add_f32 v[178:179], v[178:179], v[50:51]
	v_exp_f32_e32 v54, v54
	v_exp_f32_e32 v55, v55
	v_pk_add_f32 v[178:179], v[178:179], v[52:53]
	v_exp_f32_e32 v56, v56
	v_exp_f32_e32 v57, v57
	v_pk_add_f32 v[178:179], v[178:179], v[54:55]
	v_exp_f32_e32 v58, v58
	v_exp_f32_e32 v59, v59
	v_pk_add_f32 v[178:179], v[178:179], v[56:57]
	v_exp_f32_e32 v60, v60
	v_exp_f32_e32 v61, v61
	v_pk_add_f32 v[178:179], v[178:179], v[58:59]
	v_exp_f32_e32 v62, v62
	v_exp_f32_e32 v63, v63
	v_pk_add_f32 v[178:179], v[178:179], v[60:61]
	v_exp_f32_e32 v64, v64
	v_exp_f32_e32 v65, v65
	v_pk_add_f32 v[178:179], v[178:179], v[62:63]
	v_exp_f32_e32 v66, v66
	v_exp_f32_e32 v67, v67
	v_pk_add_f32 v[178:179], v[178:179], v[64:65]
	v_exp_f32_e32 v68, v68
	v_exp_f32_e32 v69, v69
	v_pk_add_f32 v[178:179], v[178:179], v[66:67]
	v_exp_f32_e32 v70, v70
	v_exp_f32_e32 v71, v71
	v_pk_add_f32 v[178:179], v[178:179], v[68:69]
	v_exp_f32_e32 v72, v72
	v_exp_f32_e32 v73, v73
	v_pk_add_f32 v[178:179], v[178:179], v[70:71]
	v_exp_f32_e32 v74, v74
	v_exp_f32_e32 v75, v75
	v_pk_add_f32 v[178:179], v[178:179], v[72:73]
	v_exp_f32_e32 v76, v76
	v_exp_f32_e32 v77, v77
	v_pk_add_f32 v[178:179], v[178:179], v[74:75]
; __device__ __forceinline__ void phase_attn(KP kp, int l, unsigned char* shm) {
;     ...
;       float sum = 0.f;
; #pragma unroll
;       for (int kb = 0; kb < 16; ++kb)
; #pragma unroll
;         for (int j = 0; j < 4; ++j) { lg[kb][j] = __builtin_amdgcn_exp2f(lg[kb][j] - mx); sum += lg[kb][j]; }
;       sum += __shfl_xor(sum, 16);
;       sum += __shfl_xor(sum, 32);
;       const float inv = 1.f / sum;
;       bf16x8 pf[8];
; #pragma unroll
;       for (int s8 = 0; s8 < 8; ++s8) {
;         u32x4 pk;
;         pk[0] = cvt_pk_bf16(lg[2 * s8][0], lg[2 * s8][1]);
;         pk[1] = cvt_pk_bf16(lg[2 * s8][2], lg[2 * s8][3]);
;         pk[2] = cvt_pk_bf16(lg[2 * s8 + 1][0], lg[2 * s8 + 1][1]);
;         pk[3] = cvt_pk_bf16(lg[2 * s8 + 1][2], lg[2 * s8 + 1][3]);
;         pf[s8] = __builtin_bit_cast(bf16x8, pk);
;       }
;       f32x4 oacc[4];
; #pragma unroll
;       for (int c = 0; c < 4; ++c) oacc[c] = (f32x4){0.f, 0.f, 0.f, 0.f};
;       for (int repV = 0; repV < ((PROBE & 256) ? 2 : 1); ++repV)
;       {
;         if (repV) {
; #pragma unroll
;           for (int c = 0; c < 4; ++c) oacc[c] = (f32x4){0.f, 0.f, 0.f, 0.f};
;         }
; #pragma unroll
;         for (int i = 16; i < 32; ++i) {
;           const int idx = selw[i * 8 + ks8];
;           vr[i] = *(const u32x4*)(vbase + (size_t)idx * 128 + kvh * 64 + dc * 8);
;         }
; #pragma unroll
;         for (int s8 = 0; s8 < 8; ++s8) {
; #pragma unroll
;           for (int it = 0; it < 4; ++it) *(u32x4*)(tileb + (it * 8 + ks8) * 144 + dc * 16) = vr[s8 * 4 + it];
;           u32x2 t0, t1, t2, t3, t4, t5, t6, t7;
;           asm volatile(
;               "ds_read_b64_tr_b16 %0, %8\n\tds_read_b64_tr_b16 %1, %8 offset:2304\n\t"
;               "ds_read_b64_tr_b16 %2, %8 offset:32\n\tds_read_b64_tr_b16 %3, %8 offset:2336\n\t"
;               "ds_read_b64_tr_b16 %4, %8 offset:64\n\tds_read_b64_tr_b16 %5, %8 offset:2368\n\t"
;               "ds_read_b64_tr_b16 %6, %8 offset:96\n\tds_read_b64_tr_b16 %7, %8 offset:2400\n\t"
;               "s_waitcnt lgkmcnt(0)"
;               : "=&v"(t0), "=&v"(t1), "=&v"(t2), "=&v"(t3), "=&v"(t4), "=&v"(t5), "=&v"(t6), "=&v"(t7)
;               : "v"(tr_addr)
;               : "memory");
;           const bf16x8 a0 = __builtin_bit_cast(bf16x8, (u32x4){t0[0], t0[1], t1[0], t1[1]});
;           const bf16x8 a1 = __builtin_bit_cast(bf16x8, (u32x4){t2[0], t2[1], t3[0], t3[1]});
	v_exp_f32_e32 v78, v78
	v_exp_f32_e32 v79, v79
	v_pk_add_f32 v[178:179], v[178:179], v[76:77]
	v_exp_f32_e32 v80, v80
	v_exp_f32_e32 v81, v81
	v_pk_add_f32 v[178:179], v[178:179], v[78:79]
	v_exp_f32_e32 v82, v82
	v_exp_f32_e32 v83, v83
	v_pk_add_f32 v[178:179], v[178:179], v[80:81]
	v_exp_f32_e32 v84, v84
	v_exp_f32_e32 v85, v85
	v_pk_add_f32 v[178:179], v[178:179], v[82:83]
	v_exp_f32_e32 v86, v86
	v_exp_f32_e32 v87, v87
	v_pk_add_f32 v[178:179], v[178:179], v[84:85]
	v_exp_f32_e32 v88, v88
	v_exp_f32_e32 v89, v89
	v_pk_add_f32 v[178:179], v[178:179], v[86:87]
	v_exp_f32_e32 v90, v90
	v_exp_f32_e32 v91, v91
	v_pk_add_f32 v[178:179], v[178:179], v[88:89]
	v_exp_f32_e32 v92, v92
	v_exp_f32_e32 v93, v93
	v_pk_add_f32 v[178:179], v[178:179], v[90:91]
	v_exp_f32_e32 v94, v94
	v_exp_f32_e32 v95, v95
	v_pk_add_f32 v[178:179], v[178:179], v[92:93]
	s_nop 0
	v_pk_add_f32 v[178:179], v[178:179], v[94:95]
	v_add_f32_e32 v210, v178, v179
	ds_bpermute_b32 v197, v191, v210
	v_cvt_pk_bf16_f32 v96, v32, v33
	v_cvt_pk_bf16_f32 v97, v34, v35
	v_cvt_pk_bf16_f32 v98, v36, v37
	v_cvt_pk_bf16_f32 v99, v38, v39
	v_cvt_pk_bf16_f32 v100, v40, v41
	v_cvt_pk_bf16_f32 v101, v42, v43
	v_cvt_pk_bf16_f32 v102, v44, v45
	v_cvt_pk_bf16_f32 v103, v46, v47
	v_cvt_pk_bf16_f32 v104, v48, v49
	v_cvt_pk_bf16_f32 v105, v50, v51
	v_cvt_pk_bf16_f32 v106, v52, v53
	v_cvt_pk_bf16_f32 v107, v54, v55
	v_cvt_pk_bf16_f32 v108, v56, v57
	v_cvt_pk_bf16_f32 v109, v58, v59
	v_cvt_pk_bf16_f32 v110, v60, v61
	v_cvt_pk_bf16_f32 v111, v62, v63
	s_waitcnt lgkmcnt(0)
	v_add_f32_e32 v210, v210, v197
	ds_bpermute_b32 v197, v192, v210
	v_cvt_pk_bf16_f32 v112, v64, v65
	v_cvt_pk_bf16_f32 v113, v66, v67
	v_cvt_pk_bf16_f32 v114, v68, v69
	v_cvt_pk_bf16_f32 v115, v70, v71
	v_cvt_pk_bf16_f32 v116, v72, v73
	v_cvt_pk_bf16_f32 v117, v74, v75
	v_cvt_pk_bf16_f32 v118, v76, v77
	v_cvt_pk_bf16_f32 v119, v78, v79
	v_cvt_pk_bf16_f32 v120, v80, v81
	v_cvt_pk_bf16_f32 v121, v82, v83
	v_cvt_pk_bf16_f32 v122, v84, v85
	v_cvt_pk_bf16_f32 v123, v86, v87
	v_cvt_pk_bf16_f32 v124, v88, v89
	v_cvt_pk_bf16_f32 v125, v90, v91
	v_cvt_pk_bf16_f32 v126, v92, v93
	v_cvt_pk_bf16_f32 v127, v94, v95
	s_waitcnt lgkmcnt(0)
	v_add_f32_e32 v210, v210, v197
	v_rcp_f32_e32 v208, v210
	s_waitcnt vmcnt(8)
	ds_read_b64_tr_b16 v[160:161], v182 offset:0
	ds_read_b64_tr_b16 v[162:163], v182 offset:2048
	ds_read_b64_tr_b16 v[164:165], v183 offset:0
	ds_read_b64_tr_b16 v[166:167], v183 offset:2048
	ds_read_b64_tr_b16 v[168:169], v184 offset:0
	ds_read_b64_tr_b16 v[170:171], v184 offset:2048
	ds_read_b64_tr_b16 v[172:173], v185 offset:0
	ds_read_b64_tr_b16 v[174:175], v185 offset:2048
	s_mov_b32 m0, s49
	s_nop 0
	global_load_lds_dwordx4 v12, s[22:23]
	global_load_lds_dwordx4 v13, s[22:23] offset:1024
	global_load_lds_dwordx4 v14, s[22:23] offset:2048
	global_load_lds_dwordx4 v15, s[22:23] offset:3072
	s_waitcnt lgkmcnt(0)
	v_mfma_f32_16x16x32_bf16 v[128:131], v[160:163], v[96:99], 0
	v_mfma_f32_16x16x32_bf16 v[132:135], v[164:167], v[96:99], 0
	v_mfma_f32_16x16x32_bf16 v[136:139], v[168:171], v[96:99], 0
	v_mfma_f32_16x16x32_bf16 v[140:143], v[172:175], v[96:99], 0
	s_waitcnt vmcnt(8)
	ds_read_b64_tr_b16 v[160:161], v182 offset:4096
	ds_read_b64_tr_b16 v[162:163], v182 offset:6144
	ds_read_b64_tr_b16 v[164:165], v183 offset:4096
	ds_read_b64_tr_b16 v[166:167], v183 offset:6144
	ds_read_b64_tr_b16 v[168:169], v184 offset:4096
	ds_read_b64_tr_b16 v[170:171], v184 offset:6144
	ds_read_b64_tr_b16 v[172:173], v185 offset:4096
	ds_read_b64_tr_b16 v[174:175], v185 offset:6144
	s_mov_b32 m0, s46
	s_nop 0
	global_load_lds_dwordx4 v16, s[22:23]
	global_load_lds_dwordx4 v18, s[22:23] offset:1024
	global_load_lds_dwordx4 v19, s[22:23] offset:2048
	global_load_lds_dwordx4 v20, s[22:23] offset:3072
	s_waitcnt lgkmcnt(0)
	v_mfma_f32_16x16x32_bf16 v[128:131], v[160:163], v[100:103], v[128:131]
	v_mfma_f32_16x16x32_bf16 v[132:135], v[164:167], v[100:103], v[132:135]
	v_mfma_f32_16x16x32_bf16 v[136:139], v[168:171], v[100:103], v[136:139]
	v_mfma_f32_16x16x32_bf16 v[140:143], v[172:175], v[100:103], v[140:143]
	s_waitcnt vmcnt(8)
	ds_read_b64_tr_b16 v[160:161], v182 offset:8192
	ds_read_b64_tr_b16 v[162:163], v182 offset:10240
	ds_read_b64_tr_b16 v[164:165], v183 offset:8192
	ds_read_b64_tr_b16 v[166:167], v183 offset:10240
	ds_read_b64_tr_b16 v[168:169], v184 offset:8192
	ds_read_b64_tr_b16 v[170:171], v184 offset:10240
	ds_read_b64_tr_b16 v[172:173], v185 offset:8192
	ds_read_b64_tr_b16 v[174:175], v185 offset:10240
	s_mov_b32 m0, s47
	s_nop 0
	global_load_lds_dwordx4 v21, s[22:23]
	global_load_lds_dwordx4 v22, s[22:23] offset:1024
	global_load_lds_dwordx4 v23, s[22:23] offset:2048
	global_load_lds_dwordx4 v24, s[22:23] offset:3072
	s_waitcnt lgkmcnt(0)
	v_mfma_f32_16x16x32_bf16 v[128:131], v[160:163], v[104:107], v[128:131]
	v_mfma_f32_16x16x32_bf16 v[132:135], v[164:167], v[104:107], v[132:135]
	v_mfma_f32_16x16x32_bf16 v[136:139], v[168:171], v[104:107], v[136:139]
	v_mfma_f32_16x16x32_bf16 v[140:143], v[172:175], v[104:107], v[140:143]
	s_waitcnt vmcnt(8)
	ds_read_b64_tr_b16 v[160:161], v182 offset:12288
	ds_read_b64_tr_b16 v[162:163], v182 offset:14336
	ds_read_b64_tr_b16 v[164:165], v183 offset:12288
	ds_read_b64_tr_b16 v[166:167], v183 offset:14336
	ds_read_b64_tr_b16 v[168:169], v184 offset:12288
	ds_read_b64_tr_b16 v[170:171], v184 offset:14336
	ds_read_b64_tr_b16 v[172:173], v185 offset:12288
	ds_read_b64_tr_b16 v[174:175], v185 offset:14336
	s_mov_b32 m0, s48
	s_nop 0
	global_load_lds_dwordx4 v25, s[22:23]
	global_load_lds_dwordx4 v26, s[22:23] offset:1024
	global_load_lds_dwordx4 v27, s[22:23] offset:2048
	global_load_lds_dwordx4 v28, s[22:23] offset:3072
	s_waitcnt lgkmcnt(0)
; __device__ __forceinline__ void phase_attn(KP kp, int l, unsigned char* shm) {
;     ...
;         for (int i = 16; i < 32; ++i) {
;           const int idx = selw[i * 8 + ks8];
;           vr[i] = *(const u32x4*)(vbase + (size_t)idx * 128 + kvh * 64 + dc * 8);
;         }
; #pragma unroll
;         for (int s8 = 0; s8 < 8; ++s8) {
; #pragma unroll
;           for (int it = 0; it < 4; ++it) *(u32x4*)(tileb + (it * 8 + ks8) * 144 + dc * 16) = vr[s8 * 4 + it];
;           u32x2 t0, t1, t2, t3, t4, t5, t6, t7;
;           asm volatile(
;               "ds_read_b64_tr_b16 %0, %8\n\tds_read_b64_tr_b16 %1, %8 offset:2304\n\t"
;               "ds_read_b64_tr_b16 %2, %8 offset:32\n\tds_read_b64_tr_b16 %3, %8 offset:2336\n\t"
;               "ds_read_b64_tr_b16 %4, %8 offset:64\n\tds_read_b64_tr_b16 %5, %8 offset:2368\n\t"
;               "ds_read_b64_tr_b16 %6, %8 offset:96\n\tds_read_b64_tr_b16 %7, %8 offset:2400\n\t"
;               "s_waitcnt lgkmcnt(0)"
;               : "=&v"(t0), "=&v"(t1), "=&v"(t2), "=&v"(t3), "=&v"(t4), "=&v"(t5), "=&v"(t6), "=&v"(t7)
;               : "v"(tr_addr)
;               : "memory");
;           const bf16x8 a0 = __builtin_bit_cast(bf16x8, (u32x4){t0[0], t0[1], t1[0], t1[1]});
;           const bf16x8 a1 = __builtin_bit_cast(bf16x8, (u32x4){t2[0], t2[1], t3[0], t3[1]});
;           const bf16x8 a2 = __builtin_bit_cast(bf16x8, (u32x4){t4[0], t4[1], t5[0], t5[1]});
;           const bf16x8 a3 = __builtin_bit_cast(bf16x8, (u32x4){t6[0], t6[1], t7[0], t7[1]});
;           oacc[0] = __builtin_amdgcn_mfma_f32_16x16x32_bf16(a0, pf[s8], oacc[0], 0, 0, 0);
;           oacc[1] = __builtin_amdgcn_mfma_f32_16x16x32_bf16(a1, pf[s8], oacc[1], 0, 0, 0);
;           oacc[2] = __builtin_amdgcn_mfma_f32_16x16x32_bf16(a2, pf[s8], oacc[2], 0, 0, 0);
;           oacc[3] = __builtin_amdgcn_mfma_f32_16x16x32_bf16(a3, pf[s8], oacc[3], 0, 0, 0);
;           if (kvh == 0 && s8 == 3) {
; #pragma unroll
;             for (int k8 = 0; k8 < 8; ++k8) {
;               const int idx = selw[k8 * 16 + nn];
;               const bf16_t* kp = kbase + (size_t)idx * 128 + 64 + kg * 8;
;               kpre[k8][0] = *(const bf16x8*)kp;
;               kpre[k8][1] = *(const bf16x8*)(kp + 32);
;             }
;           }
;         }
;         __builtin_amdgcn_sched_barrier(0);
;       }
;       if (nn < 4) {
; #pragma unroll
;         for (int c = 0; c < 4; ++c) {
	v_mfma_f32_16x16x32_bf16 v[128:131], v[160:163], v[108:111], v[128:131]
	v_mfma_f32_16x16x32_bf16 v[132:135], v[164:167], v[108:111], v[132:135]
	v_mfma_f32_16x16x32_bf16 v[136:139], v[168:171], v[108:111], v[136:139]
	v_mfma_f32_16x16x32_bf16 v[140:143], v[172:175], v[108:111], v[140:143]
	s_waitcnt vmcnt(8)
	ds_read_b64_tr_b16 v[160:161], v182 offset:0
	ds_read_b64_tr_b16 v[162:163], v182 offset:2048
	ds_read_b64_tr_b16 v[164:165], v183 offset:0
	ds_read_b64_tr_b16 v[166:167], v183 offset:2048
	ds_read_b64_tr_b16 v[168:169], v184 offset:0
	ds_read_b64_tr_b16 v[170:171], v184 offset:2048
	ds_read_b64_tr_b16 v[172:173], v185 offset:0
	ds_read_b64_tr_b16 v[174:175], v185 offset:2048
	s_mov_b32 m0, s49
	s_nop 0
	global_load_lds_dwordx4 v29, s[22:23]
	global_load_lds_dwordx4 v30, s[22:23] offset:1024
	global_load_lds_dwordx4 v31, s[22:23] offset:2048
	global_load_lds_dwordx4 v219, s[22:23] offset:3072
	s_waitcnt lgkmcnt(0)
	v_mfma_f32_16x16x32_bf16 v[128:131], v[160:163], v[112:115], v[128:131]
	v_mfma_f32_16x16x32_bf16 v[132:135], v[164:167], v[112:115], v[132:135]
	v_mfma_f32_16x16x32_bf16 v[136:139], v[168:171], v[112:115], v[136:139]
	v_mfma_f32_16x16x32_bf16 v[140:143], v[172:175], v[112:115], v[140:143]
	s_waitcnt vmcnt(8)
	ds_read_b64_tr_b16 v[160:161], v182 offset:4096
	ds_read_b64_tr_b16 v[162:163], v182 offset:6144
	ds_read_b64_tr_b16 v[164:165], v183 offset:4096
	ds_read_b64_tr_b16 v[166:167], v183 offset:6144
	ds_read_b64_tr_b16 v[168:169], v184 offset:4096
	ds_read_b64_tr_b16 v[170:171], v184 offset:6144
	ds_read_b64_tr_b16 v[172:173], v185 offset:4096
	ds_read_b64_tr_b16 v[174:175], v185 offset:6144
	s_mov_b32 m0, s46
	s_nop 0
	global_load_lds_dwordx4 v0, s[24:25]
	global_load_lds_dwordx4 v1, s[24:25] offset:1024
	global_load_lds_dwordx4 v2, s[24:25] offset:2048
	global_load_lds_dwordx4 v3, s[24:25] offset:3072
	s_waitcnt lgkmcnt(0)
	v_mfma_f32_16x16x32_bf16 v[128:131], v[160:163], v[116:119], v[128:131]
	v_mfma_f32_16x16x32_bf16 v[132:135], v[164:167], v[116:119], v[132:135]
	v_mfma_f32_16x16x32_bf16 v[136:139], v[168:171], v[116:119], v[136:139]
	v_mfma_f32_16x16x32_bf16 v[140:143], v[172:175], v[116:119], v[140:143]
	s_waitcnt vmcnt(8)
	ds_read_b64_tr_b16 v[160:161], v182 offset:8192
	ds_read_b64_tr_b16 v[162:163], v182 offset:10240
	ds_read_b64_tr_b16 v[164:165], v183 offset:8192
	ds_read_b64_tr_b16 v[166:167], v183 offset:10240
	ds_read_b64_tr_b16 v[168:169], v184 offset:8192
	ds_read_b64_tr_b16 v[170:171], v184 offset:10240
	ds_read_b64_tr_b16 v[172:173], v185 offset:8192
	ds_read_b64_tr_b16 v[174:175], v185 offset:10240
	s_mov_b32 m0, s47
	s_nop 0
	global_load_lds_dwordx4 v4, s[24:25]
	global_load_lds_dwordx4 v5, s[24:25] offset:1024
	global_load_lds_dwordx4 v6, s[24:25] offset:2048
	global_load_lds_dwordx4 v7, s[24:25] offset:3072
	s_waitcnt lgkmcnt(0)
	v_mfma_f32_16x16x32_bf16 v[128:131], v[160:163], v[120:123], v[128:131]
	v_mfma_f32_16x16x32_bf16 v[132:135], v[164:167], v[120:123], v[132:135]
	v_mfma_f32_16x16x32_bf16 v[136:139], v[168:171], v[120:123], v[136:139]
	v_mfma_f32_16x16x32_bf16 v[140:143], v[172:175], v[120:123], v[140:143]
	s_waitcnt vmcnt(8)
	ds_read_b64_tr_b16 v[160:161], v182 offset:12288
	ds_read_b64_tr_b16 v[162:163], v182 offset:14336
	ds_read_b64_tr_b16 v[164:165], v183 offset:12288
	ds_read_b64_tr_b16 v[166:167], v183 offset:14336
	ds_read_b64_tr_b16 v[168:169], v184 offset:12288
	ds_read_b64_tr_b16 v[170:171], v184 offset:14336
	ds_read_b64_tr_b16 v[172:173], v185 offset:12288
	ds_read_b64_tr_b16 v[174:175], v185 offset:14336
	s_mov_b32 m0, s48
	s_nop 0
	global_load_lds_dwordx4 v8, s[24:25]
	global_load_lds_dwordx4 v9, s[24:25] offset:1024
	global_load_lds_dwordx4 v10, s[24:25] offset:2048
	global_load_lds_dwordx4 v11, s[24:25] offset:3072
	s_waitcnt lgkmcnt(0)
	v_mfma_f32_16x16x32_bf16 v[128:131], v[160:163], v[124:127], v[128:131]
	v_mfma_f32_16x16x32_bf16 v[132:135], v[164:167], v[124:127], v[132:135]
	v_mfma_f32_16x16x32_bf16 v[136:139], v[168:171], v[124:127], v[136:139]
	v_mfma_f32_16x16x32_bf16 v[140:143], v[172:175], v[124:127], v[140:143]
	s_nop 7
	s_nop 3
	v_mul_f32_e32 v128, v208, v128
	v_mul_f32_e32 v129, v208, v129
	v_mul_f32_e32 v130, v208, v130
	v_mul_f32_e32 v131, v208, v131
	v_cvt_pk_bf16_f32 v200, v128, v129
	v_cvt_pk_bf16_f32 v201, v130, v131
	v_mul_f32_e32 v132, v208, v132
	v_mul_f32_e32 v133, v208, v133
	v_mul_f32_e32 v134, v208, v134
	v_mul_f32_e32 v135, v208, v135
	v_cvt_pk_bf16_f32 v202, v132, v133
	v_cvt_pk_bf16_f32 v203, v134, v135
	v_mul_f32_e32 v136, v208, v136
	v_mul_f32_e32 v137, v208, v137
	v_mul_f32_e32 v138, v208, v138
	v_mul_f32_e32 v139, v208, v139
	v_cvt_pk_bf16_f32 v204, v136, v137
	v_cvt_pk_bf16_f32 v205, v138, v139
	v_mul_f32_e32 v140, v208, v140
	v_mul_f32_e32 v141, v208, v141
	v_mul_f32_e32 v142, v208, v142
	v_mul_f32_e32 v143, v208, v143
	v_cvt_pk_bf16_f32 v206, v140, v141
	v_cvt_pk_bf16_f32 v207, v142, v143
	s_mov_b64 exec, s[42:43]
	global_store_dwordx2 v190, v[200:201], s[34:35] offset:0
	global_store_dwordx2 v190, v[202:203], s[34:35] offset:32
	global_store_dwordx2 v190, v[204:205], s[34:35] offset:64
	global_store_dwordx2 v190, v[206:207], s[34:35] offset:96
	s_mov_b64 exec, -1
	s_waitcnt vmcnt(12)
	ds_read_b128 v[160:163], v180 offset:0
	ds_read_b128 v[164:167], v181 offset:0
	ds_read_b128 v[168:171], v180 offset:2048
	ds_read_b128 v[172:175], v181 offset:2048
	s_add_i32 s50, s2, s4
	s_cmp_lt_i32 s50, 0x8200
	s_cselect_b32 s53, s50, s2
	s_mov_b32 s51, s53
	s_cmp_lg_u32 s5, 0
	s_cbranch_scc1 .Lattn_noswz_7
	s_cmp_ge_i32 s53, 0x8000
	s_cbranch_scc1 .Lattn_noswz_7
	s_lshl_b32 s6, s53, 9
	s_and_b32 s6, s6, 0x7000
	s_lshr_b32 s7, s53, 3
	s_and_b32 s8, s7, 0xffffff00
	s_and_b32 s7, s7, 0xf8
	s_or_b32 s6, s6, s8
	s_or_b32 s6, s6, s7
	s_and_b32 s7, s53, 7
	s_or_b32 s51, s6, s7

; __device__ __forceinline__ void phase_attn(KP kp, int l, unsigned char* shm) {
;     ...
;     if (r < MP) {
;       const int b = r >> 12, t = r & 4095;
;       kbase = (const bf16_t*)(ws + W_KP) + (size_t)b * 4096 * 128;
;       vbase = (const bf16_t*)(ws + W_VP) + (size_t)b * 4096 * 128;
;       n = ((t >> 6) + 1) * 64;
;     } else {
;       const int sb = (r - MP) >> 5;
;       kbase = (const bf16_t*)(ws + W_KS) + (size_t)(l * 16 + sb) * 2080 * 128;
;       vbase = (const bf16_t*)(ws + W_VS) + (size_t)(l * 16 + sb) * 2080 * 128;
;       n = 2080;
;     }
;     const int cnt = n < 256 ? n : 256;
;     {
;       u32x2 sv = *(const u32x2*)(SEL + (size_t)r * 256 + lane * 4);
;     ...
;         for (int hb = 0; hb < 2; ++hb) {
;           bf16x8 ka[8][2];
;           if (kvh == 1 && hb == 0) {
; #pragma unroll
;             for (int k8 = 0; k8 < 8; ++k8) { ka[k8][0] = kpre[k8][0]; ka[k8][1] = kpre[k8][1]; }
;           } else {
; #pragma unroll
;             for (int k8 = 0; k8 < 8; ++k8) {
;               const int idx = selw[(hb * 8 + k8) * 16 + nn];
;               const bf16_t* kp = kbase + (size_t)idx * 128 + kvh * 64 + kg * 8;
;               ka[k8][0] = *(const bf16x8*)kp;
;               ka[k8][1] = *(const bf16x8*)(kp + 32);
;             }
;           }
;           __builtin_amdgcn_sched_barrier(0);
; #pragma unroll
;           for (int k8 = 0; k8 < 8; ++k8) {
;             f32x4 a = (f32x4){0.f, 0.f, 0.f, 0.f};
;             a = __builtin_amdgcn_mfma_f32_16x16x32_bf16(ka[k8][0], bq0, a, 0, 0, 0);
;             a = __builtin_amdgcn_mfma_f32_16x16x32_bf16(ka[k8][1], bq1, a, 0, 0, 0);
;             lg[hb * 8 + k8] = a;
;           }
;           __builtin_amdgcn_sched_barrier(0);
.Lattn_join_9:
	s_add_u32 s28, s0, s7
	s_addc_u32 s29, s1, 0
	s_add_u32 s30, s0, s8
	s_addc_u32 s31, s1, 0
	s_lshl_b32 s6, s51, 9
	s_add_u32 s6, s6, 0x1b3c2000
	s_add_u32 s38, s0, s6
	s_addc_u32 s39, s1, 0
	s_lshl_b32 s6, s51, 10
	s_add_u32 s7, s6, 0x7ac0000
	s_add_u32 s40, s0, s7
	s_addc_u32 s41, s1, 0
	s_add_u32 s7, s6, 0x1c402000
	s_add_u32 s36, s0, s7
	s_addc_u32 s37, s1, 0
	global_load_dwordx2 v[198:199], v188, s[38:39]
	s_mov_b32 m0, s49
	s_nop 0
	global_load_lds_dwordx4 v12, s[24:25]
	global_load_lds_dwordx4 v13, s[24:25] offset:1024
	global_load_lds_dwordx4 v14, s[24:25] offset:2048
	global_load_lds_dwordx4 v15, s[24:25] offset:3072
	s_waitcnt lgkmcnt(0)
	v_mfma_f32_16x16x32_bf16 v[32:35], v[160:163], v[152:155], 0
	v_mfma_f32_16x16x32_bf16 v[36:39], v[168:171], v[152:155], 0
	v_mfma_f32_16x16x32_bf16 v[32:35], v[164:167], v[156:159], v[32:35]
	v_mfma_f32_16x16x32_bf16 v[36:39], v[172:175], v[156:159], v[36:39]
	s_waitcnt vmcnt(13)
	ds_read_b128 v[160:163], v180 offset:4096
	ds_read_b128 v[164:167], v181 offset:4096
	ds_read_b128 v[168:171], v180 offset:6144
	ds_read_b128 v[172:175], v181 offset:6144
	s_mov_b32 m0, s46
	s_nop 0
	global_load_lds_dwordx4 v16, s[24:25]
	global_load_lds_dwordx4 v18, s[24:25] offset:1024
	global_load_lds_dwordx4 v19, s[24:25] offset:2048
	global_load_lds_dwordx4 v20, s[24:25] offset:3072
	s_waitcnt lgkmcnt(0)
	v_mfma_f32_16x16x32_bf16 v[40:43], v[160:163], v[152:155], 0
	v_mfma_f32_16x16x32_bf16 v[44:47], v[168:171], v[152:155], 0
	v_mfma_f32_16x16x32_bf16 v[40:43], v[164:167], v[156:159], v[40:43]
	v_mfma_f32_16x16x32_bf16 v[44:47], v[172:175], v[156:159], v[44:47]
	s_waitcnt vmcnt(13)
	ds_read_b128 v[160:163], v180 offset:8192
	ds_read_b128 v[164:167], v181 offset:8192
	ds_read_b128 v[168:171], v180 offset:10240
	ds_read_b128 v[172:175], v181 offset:10240
	s_mov_b32 m0, s47
	s_nop 0
	global_load_lds_dwordx4 v21, s[24:25]
	global_load_lds_dwordx4 v22, s[24:25] offset:1024
	global_load_lds_dwordx4 v23, s[24:25] offset:2048
	global_load_lds_dwordx4 v24, s[24:25] offset:3072
	s_waitcnt lgkmcnt(0)
	v_mfma_f32_16x16x32_bf16 v[48:51], v[160:163], v[152:155], 0
	v_mfma_f32_16x16x32_bf16 v[52:55], v[168:171], v[152:155], 0
	v_mfma_f32_16x16x32_bf16 v[48:51], v[164:167], v[156:159], v[48:51]
	v_mfma_f32_16x16x32_bf16 v[52:55], v[172:175], v[156:159], v[52:55]
	s_waitcnt vmcnt(8)
	ds_read_b128 v[160:163], v180 offset:12288
	ds_read_b128 v[164:167], v181 offset:12288
	ds_read_b128 v[168:171], v180 offset:14336
	ds_read_b128 v[172:175], v181 offset:14336
	s_mov_b32 m0, s48
	s_nop 0
	global_load_lds_dwordx4 v25, s[24:25]
	global_load_lds_dwordx4 v26, s[24:25] offset:1024
	global_load_lds_dwordx4 v27, s[24:25] offset:2048
	global_load_lds_dwordx4 v28, s[24:25] offset:3072
	s_waitcnt lgkmcnt(0)
	v_mfma_f32_16x16x32_bf16 v[56:59], v[160:163], v[152:155], 0
	v_mfma_f32_16x16x32_bf16 v[60:63], v[168:171], v[152:155], 0
	v_mfma_f32_16x16x32_bf16 v[56:59], v[164:167], v[156:159], v[56:59]
	v_mfma_f32_16x16x32_bf16 v[60:63], v[172:175], v[156:159], v[60:63]
	s_waitcnt vmcnt(8)
	ds_read_b128 v[160:163], v180 offset:0
	ds_read_b128 v[164:167], v181 offset:0
	ds_read_b128 v[168:171], v180 offset:2048
	ds_read_b128 v[172:175], v181 offset:2048
	s_mov_b32 m0, s49
	s_nop 0
	global_load_lds_dwordx4 v29, s[24:25]
	global_load_lds_dwordx4 v30, s[24:25] offset:1024
	global_load_lds_dwordx4 v31, s[24:25] offset:2048
	global_load_lds_dwordx4 v219, s[24:25] offset:3072
	s_waitcnt lgkmcnt(0)
	v_mfma_f32_16x16x32_bf16 v[64:67], v[160:163], v[152:155], 0
	v_mfma_f32_16x16x32_bf16 v[68:71], v[168:171], v[152:155], 0
	v_mfma_f32_16x16x32_bf16 v[64:67], v[164:167], v[156:159], v[64:67]
	v_mfma_f32_16x16x32_bf16 v[68:71], v[172:175], v[156:159], v[68:71]
	s_waitcnt vmcnt(8)
	ds_read_b128 v[160:163], v180 offset:4096
	ds_read_b128 v[164:167], v181 offset:4096
	ds_read_b128 v[168:171], v180 offset:6144
	ds_read_b128 v[172:175], v181 offset:6144
	s_mov_b32 m0, s46
	s_nop 0
	global_load_lds_dwordx4 v0, s[26:27]
	global_load_lds_dwordx4 v1, s[26:27] offset:1024
	global_load_lds_dwordx4 v2, s[26:27] offset:2048
	global_load_lds_dwordx4 v3, s[26:27] offset:3072
	s_waitcnt lgkmcnt(0)
	v_mfma_f32_16x16x32_bf16 v[72:75], v[160:163], v[152:155], 0
	v_mfma_f32_16x16x32_bf16 v[76:79], v[168:171], v[152:155], 0
	v_mfma_f32_16x16x32_bf16 v[72:75], v[164:167], v[156:159], v[72:75]
	v_mfma_f32_16x16x32_bf16 v[76:79], v[172:175], v[156:159], v[76:79]
	s_waitcnt vmcnt(8)
	ds_read_b128 v[160:163], v180 offset:8192
	ds_read_b128 v[164:167], v181 offset:8192
	ds_read_b128 v[168:171], v180 offset:10240
	ds_read_b128 v[172:175], v181 offset:10240
	s_mov_b32 m0, s47
	s_nop 0
	global_load_lds_dwordx4 v4, s[26:27]
	global_load_lds_dwordx4 v5, s[26:27] offset:1024
	global_load_lds_dwordx4 v6, s[26:27] offset:2048
	global_load_lds_dwordx4 v7, s[26:27] offset:3072
	s_waitcnt lgkmcnt(0)
	v_mfma_f32_16x16x32_bf16 v[80:83], v[160:163], v[152:155], 0
	v_mfma_f32_16x16x32_bf16 v[84:87], v[168:171], v[152:155], 0
	v_mfma_f32_16x16x32_bf16 v[80:83], v[164:167], v[156:159], v[80:83]
	v_mfma_f32_16x16x32_bf16 v[84:87], v[172:175], v[156:159], v[84:87]
	s_waitcnt vmcnt(8)
	ds_read_b128 v[160:163], v180 offset:12288
	ds_read_b128 v[164:167], v181 offset:12288
	ds_read_b128 v[168:171], v180 offset:14336
	ds_read_b128 v[172:175], v181 offset:14336
	s_mov_b32 m0, s48
	s_nop 0
	global_load_lds_dwordx4 v8, s[26:27]
	global_load_lds_dwordx4 v9, s[26:27] offset:1024
	global_load_lds_dwordx4 v10, s[26:27] offset:2048
	global_load_lds_dwordx4 v11, s[26:27] offset:3072
	s_waitcnt lgkmcnt(0)
	v_mfma_f32_16x16x32_bf16 v[88:91], v[160:163], v[152:155], 0
	v_mfma_f32_16x16x32_bf16 v[92:95], v[168:171], v[152:155], 0
	v_mfma_f32_16x16x32_bf16 v[88:91], v[164:167], v[156:159], v[88:91]
	v_mfma_f32_16x16x32_bf16 v[92:95], v[172:175], v[156:159], v[92:95]
	s_nop 7
	s_nop 3
	s_cmp_ge_u32 s44, 0x100
	s_cbranch_scc1 .Lattn_nomask_10
	s_cmp_ge_u32 s44, 0xc0
	s_cbranch_scc1 .Lattn_m192_11
	s_cmp_ge_u32 s44, 0x80
	s_cbranch_scc1 .Lattn_m128_12
	v_mov_b32_e32 v48, 0xf149f2ca
	v_mov_b32_e32 v49, 0xf149f2ca
	v_mov_b32_e32 v50, 0xf149f2ca
	v_mov_b32_e32 v51, 0xf149f2ca
	v_mov_b32_e32 v52, 0xf149f2ca
	v_mov_b32_e32 v53, 0xf149f2ca
	v_mov_b32_e32 v54, 0xf149f2ca
	v_mov_b32_e32 v55, 0xf149f2ca
	v_mov_b32_e32 v56, 0xf149f2ca
	v_mov_b32_e32 v57, 0xf149f2ca
	v_mov_b32_e32 v58, 0xf149f2ca
	v_mov_b32_e32 v59, 0xf149f2ca
	v_mov_b32_e32 v60, 0xf149f2ca
	v_mov_b32_e32 v61, 0xf149f2ca
	v_mov_b32_e32 v62, 0xf149f2ca
	v_mov_b32_e32 v63, 0xf149f2ca

; __device__ __forceinline__ void phase_attn(KP kp, int l, unsigned char* shm) {
;     ...
;       float mx = -1e30f;
; #pragma unroll
;       for (int kb = 0; kb < 16; ++kb)
; #pragma unroll
;         for (int j = 0; j < 4; ++j) {
;           const int key = kb * 16 + kg * 4 + j;
;           lg[kb][j] = key < cnt ? lg[kb][j] : -1e30f;
;           mx = fmaxf(mx, lg[kb][j]);
;         }
;       mx = fmaxf(mx, __shfl_xor(mx, 16));
;       mx = fmaxf(mx, __shfl_xor(mx, 32));
;       float sum = 0.f;
; #pragma unroll
;       for (int kb = 0; kb < 16; ++kb)
; #pragma unroll
;         for (int j = 0; j < 4; ++j) { lg[kb][j] = __builtin_amdgcn_exp2f(lg[kb][j] - mx); sum += lg[kb][j]; }
;       sum += __shfl_xor(sum, 16);
;       sum += __shfl_xor(sum, 32);
.Lattn_nomask_10:
	v_max3_f32 v176, v32, v33, v34
	v_max3_f32 v176, v176, v35, v36
	v_max3_f32 v176, v176, v37, v38
	v_max3_f32 v176, v176, v39, v40
	v_max3_f32 v176, v176, v41, v42
	v_max3_f32 v176, v176, v43, v44
	v_max3_f32 v176, v176, v45, v46
	v_max3_f32 v176, v176, v47, v48
	v_max3_f32 v176, v176, v49, v50
	v_max3_f32 v176, v176, v51, v52
	v_max3_f32 v176, v176, v53, v54
	v_max3_f32 v176, v176, v55, v56
	v_max3_f32 v176, v176, v57, v58
	v_max3_f32 v176, v176, v59, v60
	v_max3_f32 v176, v176, v61, v62
	v_max3_f32 v176, v176, v63, v64
	v_max3_f32 v176, v176, v65, v66
	v_max3_f32 v176, v176, v67, v68
	v_max3_f32 v176, v176, v69, v70
	v_max3_f32 v176, v176, v71, v72
	v_max3_f32 v176, v176, v73, v74
	v_max3_f32 v176, v176, v75, v76
	v_max3_f32 v176, v176, v77, v78
	v_max3_f32 v176, v176, v79, v80
	v_max3_f32 v176, v176, v81, v82
	v_max3_f32 v176, v176, v83, v84
	v_max3_f32 v176, v176, v85, v86
	v_max3_f32 v176, v176, v87, v88
	v_max3_f32 v176, v176, v89, v90
	v_max3_f32 v176, v176, v91, v92
	v_max3_f32 v176, v176, v93, v94
	v_max_f32_e32 v176, v176, v95
	ds_bpermute_b32 v197, v191, v176
	s_waitcnt lgkmcnt(0)
	v_max_f32_e32 v176, v176, v197
	ds_bpermute_b32 v197, v192, v176
	s_waitcnt lgkmcnt(0)
	v_max_f32_e32 v176, v176, v197
	v_mov_b32_e32 v177, v176
	v_pk_add_f32 v[32:33], v[32:33], v[176:177] neg_lo:[0,1] neg_hi:[0,1]
	v_pk_add_f32 v[34:35], v[34:35], v[176:177] neg_lo:[0,1] neg_hi:[0,1]
	v_pk_add_f32 v[36:37], v[36:37], v[176:177] neg_lo:[0,1] neg_hi:[0,1]
	v_pk_add_f32 v[38:39], v[38:39], v[176:177] neg_lo:[0,1] neg_hi:[0,1]
	v_pk_add_f32 v[40:41], v[40:41], v[176:177] neg_lo:[0,1] neg_hi:[0,1]
	v_pk_add_f32 v[42:43], v[42:43], v[176:177] neg_lo:[0,1] neg_hi:[0,1]
	v_pk_add_f32 v[44:45], v[44:45], v[176:177] neg_lo:[0,1] neg_hi:[0,1]
	v_pk_add_f32 v[46:47], v[46:47], v[176:177] neg_lo:[0,1] neg_hi:[0,1]
	v_pk_add_f32 v[48:49], v[48:49], v[176:177] neg_lo:[0,1] neg_hi:[0,1]
	v_pk_add_f32 v[50:51], v[50:51], v[176:177] neg_lo:[0,1] neg_hi:[0,1]
	v_pk_add_f32 v[52:53], v[52:53], v[176:177] neg_lo:[0,1] neg_hi:[0,1]
	v_pk_add_f32 v[54:55], v[54:55], v[176:177] neg_lo:[0,1] neg_hi:[0,1]
	v_pk_add_f32 v[56:57], v[56:57], v[176:177] neg_lo:[0,1] neg_hi:[0,1]
	v_pk_add_f32 v[58:59], v[58:59], v[176:177] neg_lo:[0,1] neg_hi:[0,1]
	v_pk_add_f32 v[60:61], v[60:61], v[176:177] neg_lo:[0,1] neg_hi:[0,1]
	v_pk_add_f32 v[62:63], v[62:63], v[176:177] neg_lo:[0,1] neg_hi:[0,1]
	v_pk_add_f32 v[64:65], v[64:65], v[176:177] neg_lo:[0,1] neg_hi:[0,1]
	v_pk_add_f32 v[66:67], v[66:67], v[176:177] neg_lo:[0,1] neg_hi:[0,1]
	v_pk_add_f32 v[68:69], v[68:69], v[176:177] neg_lo:[0,1] neg_hi:[0,1]
	v_pk_add_f32 v[70:71], v[70:71], v[176:177] neg_lo:[0,1] neg_hi:[0,1]
	v_pk_add_f32 v[72:73], v[72:73], v[176:177] neg_lo:[0,1] neg_hi:[0,1]
	v_pk_add_f32 v[74:75], v[74:75], v[176:177] neg_lo:[0,1] neg_hi:[0,1]
	v_pk_add_f32 v[76:77], v[76:77], v[176:177] neg_lo:[0,1] neg_hi:[0,1]
	v_pk_add_f32 v[78:79], v[78:79], v[176:177] neg_lo:[0,1] neg_hi:[0,1]
	v_pk_add_f32 v[80:81], v[80:81], v[176:177] neg_lo:[0,1] neg_hi:[0,1]
	v_pk_add_f32 v[82:83], v[82:83], v[176:177] neg_lo:[0,1] neg_hi:[0,1]
	v_pk_add_f32 v[84:85], v[84:85], v[176:177] neg_lo:[0,1] neg_hi:[0,1]
	v_pk_add_f32 v[86:87], v[86:87], v[176:177] neg_lo:[0,1] neg_hi:[0,1]
	v_pk_add_f32 v[88:89], v[88:89], v[176:177] neg_lo:[0,1] neg_hi:[0,1]
	v_pk_add_f32 v[90:91], v[90:91], v[176:177] neg_lo:[0,1] neg_hi:[0,1]
	v_pk_add_f32 v[92:93], v[92:93], v[176:177] neg_lo:[0,1] neg_hi:[0,1]
	v_pk_add_f32 v[94:95], v[94:95], v[176:177] neg_lo:[0,1] neg_hi:[0,1]
	v_exp_f32_e32 v32, v32
	v_exp_f32_e32 v33, v33
	v_exp_f32_e32 v34, v34
	v_exp_f32_e32 v35, v35
	v_exp_f32_e32 v36, v36
	v_exp_f32_e32 v37, v37
	v_pk_add_f32 v[178:179], v[32:33], v[34:35]
	v_exp_f32_e32 v38, v38
	v_exp_f32_e32 v39, v39
	v_pk_add_f32 v[178:179], v[178:179], v[36:37]
	v_exp_f32_e32 v40, v40
	v_exp_f32_e32 v41, v41
	v_pk_add_f32 v[178:179], v[178:179], v[38:39]
	v_exp_f32_e32 v42, v42
	v_exp_f32_e32 v43, v43
	v_pk_add_f32 v[178:179], v[178:179], v[40:41]
	v_exp_f32_e32 v44, v44
	v_exp_f32_e32 v45, v45
	v_pk_add_f32 v[178:179], v[178:179], v[42:43]
	v_exp_f32_e32 v46, v46
	v_exp_f32_e32 v47, v47
	v_pk_add_f32 v[178:179], v[178:179], v[44:45]
	v_exp_f32_e32 v48, v48
	v_exp_f32_e32 v49, v49
	v_pk_add_f32 v[178:179], v[178:179], v[46:47]
	v_exp_f32_e32 v50, v50
	v_exp_f32_e32 v51, v51
	v_pk_add_f32 v[178:179], v[178:179], v[48:49]
	v_exp_f32_e32 v52, v52
	v_exp_f32_e32 v53, v53
	v_pk_add_f32 v[178:179], v[178:179], v[50:51]
	v_exp_f32_e32 v54, v54
	v_exp_f32_e32 v55, v55
	v_pk_add_f32 v[178:179], v[178:179], v[52:53]
	v_exp_f32_e32 v56, v56
	v_exp_f32_e32 v57, v57
	v_pk_add_f32 v[178:179], v[178:179], v[54:55]
	v_exp_f32_e32 v58, v58
	v_exp_f32_e32 v59, v59
	v_pk_add_f32 v[178:179], v[178:179], v[56:57]
	v_exp_f32_e32 v60, v60
	v_exp_f32_e32 v61, v61
	v_pk_add_f32 v[178:179], v[178:179], v[58:59]
	v_exp_f32_e32 v62, v62
	v_exp_f32_e32 v63, v63
	v_pk_add_f32 v[178:179], v[178:179], v[60:61]
	v_exp_f32_e32 v64, v64
	v_exp_f32_e32 v65, v65
	v_pk_add_f32 v[178:179], v[178:179], v[62:63]
	v_exp_f32_e32 v66, v66
	v_exp_f32_e32 v67, v67
	v_pk_add_f32 v[178:179], v[178:179], v[64:65]
	v_exp_f32_e32 v68, v68
	v_exp_f32_e32 v69, v69
	v_pk_add_f32 v[178:179], v[178:179], v[66:67]
	v_exp_f32_e32 v70, v70
	v_exp_f32_e32 v71, v71
	v_pk_add_f32 v[178:179], v[178:179], v[68:69]
	v_exp_f32_e32 v72, v72
	v_exp_f32_e32 v73, v73
	v_pk_add_f32 v[178:179], v[178:179], v[70:71]
	v_exp_f32_e32 v74, v74
	v_exp_f32_e32 v75, v75
	v_pk_add_f32 v[178:179], v[178:179], v[72:73]
	v_exp_f32_e32 v76, v76
	v_exp_f32_e32 v77, v77
	v_pk_add_f32 v[178:179], v[178:179], v[74:75]
; __device__ __forceinline__ void phase_attn(KP kp, int l, unsigned char* shm) {
;     ...
;       float sum = 0.f;
; #pragma unroll
;       for (int kb = 0; kb < 16; ++kb)
; #pragma unroll
;         for (int j = 0; j < 4; ++j) { lg[kb][j] = __builtin_amdgcn_exp2f(lg[kb][j] - mx); sum += lg[kb][j]; }
;       sum += __shfl_xor(sum, 16);
;       sum += __shfl_xor(sum, 32);
;       const float inv = 1.f / sum;
;       bf16x8 pf[8];
; #pragma unroll
;       for (int s8 = 0; s8 < 8; ++s8) {
;         u32x4 pk;
;         pk[0] = cvt_pk_bf16(lg[2 * s8][0], lg[2 * s8][1]);
;         pk[1] = cvt_pk_bf16(lg[2 * s8][2], lg[2 * s8][3]);
;         pk[2] = cvt_pk_bf16(lg[2 * s8 + 1][0], lg[2 * s8 + 1][1]);
;         pk[3] = cvt_pk_bf16(lg[2 * s8 + 1][2], lg[2 * s8 + 1][3]);
;         pf[s8] = __builtin_bit_cast(bf16x8, pk);
;       }
;       f32x4 oacc[4];
; #pragma unroll
;       for (int c = 0; c < 4; ++c) oacc[c] = (f32x4){0.f, 0.f, 0.f, 0.f};
;       for (int repV = 0; repV < ((PROBE & 256) ? 2 : 1); ++repV)
;       {
;         if (repV) {
; #pragma unroll
;           for (int c = 0; c < 4; ++c) oacc[c] = (f32x4){0.f, 0.f, 0.f, 0.f};
;         }
; #pragma unroll
;         for (int i = 16; i < 32; ++i) {
;           const int idx = selw[i * 8 + ks8];
;           vr[i] = *(const u32x4*)(vbase + (size_t)idx * 128 + kvh * 64 + dc * 8);
;         }
; #pragma unroll
;         for (int s8 = 0; s8 < 8; ++s8) {
; #pragma unroll
;           for (int it = 0; it < 4; ++it) *(u32x4*)(tileb + (it * 8 + ks8) * 144 + dc * 16) = vr[s8 * 4 + it];
;           u32x2 t0, t1, t2, t3, t4, t5, t6, t7;
;           asm volatile(
;               "ds_read_b64_tr_b16 %0, %8\n\tds_read_b64_tr_b16 %1, %8 offset:2304\n\t"
;               "ds_read_b64_tr_b16 %2, %8 offset:32\n\tds_read_b64_tr_b16 %3, %8 offset:2336\n\t"
;               "ds_read_b64_tr_b16 %4, %8 offset:64\n\tds_read_b64_tr_b16 %5, %8 offset:2368\n\t"
;               "ds_read_b64_tr_b16 %6, %8 offset:96\n\tds_read_b64_tr_b16 %7, %8 offset:2400\n\t"
;               "s_waitcnt lgkmcnt(0)"
;               : "=&v"(t0), "=&v"(t1), "=&v"(t2), "=&v"(t3), "=&v"(t4), "=&v"(t5), "=&v"(t6), "=&v"(t7)
;               : "v"(tr_addr)
;               : "memory");
;           const bf16x8 a0 = __builtin_bit_cast(bf16x8, (u32x4){t0[0], t0[1], t1[0], t1[1]});
;           const bf16x8 a1 = __builtin_bit_cast(bf16x8, (u32x4){t2[0], t2[1], t3[0], t3[1]});
	v_exp_f32_e32 v78, v78
	v_exp_f32_e32 v79, v79
	v_pk_add_f32 v[178:179], v[178:179], v[76:77]
	v_exp_f32_e32 v80, v80
	v_exp_f32_e32 v81, v81
	v_pk_add_f32 v[178:179], v[178:179], v[78:79]
	v_exp_f32_e32 v82, v82
	v_exp_f32_e32 v83, v83
	v_pk_add_f32 v[178:179], v[178:179], v[80:81]
	v_exp_f32_e32 v84, v84
	v_exp_f32_e32 v85, v85
	v_pk_add_f32 v[178:179], v[178:179], v[82:83]
	v_exp_f32_e32 v86, v86
	v_exp_f32_e32 v87, v87
	v_pk_add_f32 v[178:179], v[178:179], v[84:85]
	v_exp_f32_e32 v88, v88
	v_exp_f32_e32 v89, v89
	v_pk_add_f32 v[178:179], v[178:179], v[86:87]
	v_exp_f32_e32 v90, v90
	v_exp_f32_e32 v91, v91
	v_pk_add_f32 v[178:179], v[178:179], v[88:89]
	v_exp_f32_e32 v92, v92
	v_exp_f32_e32 v93, v93
	v_pk_add_f32 v[178:179], v[178:179], v[90:91]
	v_exp_f32_e32 v94, v94
	v_exp_f32_e32 v95, v95
	v_pk_add_f32 v[178:179], v[178:179], v[92:93]
	s_nop 0
	v_pk_add_f32 v[178:179], v[178:179], v[94:95]
	v_add_f32_e32 v210, v178, v179
	ds_bpermute_b32 v197, v191, v210
	v_cvt_pk_bf16_f32 v96, v32, v33
	v_cvt_pk_bf16_f32 v97, v34, v35
	v_cvt_pk_bf16_f32 v98, v36, v37
	v_cvt_pk_bf16_f32 v99, v38, v39
	v_cvt_pk_bf16_f32 v100, v40, v41
	v_cvt_pk_bf16_f32 v101, v42, v43
	v_cvt_pk_bf16_f32 v102, v44, v45
	v_cvt_pk_bf16_f32 v103, v46, v47
	v_cvt_pk_bf16_f32 v104, v48, v49
	v_cvt_pk_bf16_f32 v105, v50, v51
	v_cvt_pk_bf16_f32 v106, v52, v53
	v_cvt_pk_bf16_f32 v107, v54, v55
	v_cvt_pk_bf16_f32 v108, v56, v57
	v_cvt_pk_bf16_f32 v109, v58, v59
	v_cvt_pk_bf16_f32 v110, v60, v61
	v_cvt_pk_bf16_f32 v111, v62, v63
	s_waitcnt lgkmcnt(0)
	v_add_f32_e32 v210, v210, v197
	ds_bpermute_b32 v197, v192, v210
	v_cvt_pk_bf16_f32 v112, v64, v65
	v_cvt_pk_bf16_f32 v113, v66, v67
	v_cvt_pk_bf16_f32 v114, v68, v69
	v_cvt_pk_bf16_f32 v115, v70, v71
	v_cvt_pk_bf16_f32 v116, v72, v73
	v_cvt_pk_bf16_f32 v117, v74, v75
	v_cvt_pk_bf16_f32 v118, v76, v77
	v_cvt_pk_bf16_f32 v119, v78, v79
	v_cvt_pk_bf16_f32 v120, v80, v81
	v_cvt_pk_bf16_f32 v121, v82, v83
	v_cvt_pk_bf16_f32 v122, v84, v85
	v_cvt_pk_bf16_f32 v123, v86, v87
	v_cvt_pk_bf16_f32 v124, v88, v89
	v_cvt_pk_bf16_f32 v125, v90, v91
	v_cvt_pk_bf16_f32 v126, v92, v93
	v_cvt_pk_bf16_f32 v127, v94, v95
	s_waitcnt lgkmcnt(0)
	v_add_f32_e32 v210, v210, v197
	v_rcp_f32_e32 v208, v210
	s_waitcnt vmcnt(8)
	ds_read_b64_tr_b16 v[160:161], v182 offset:0
	ds_read_b64_tr_b16 v[162:163], v182 offset:2048
	ds_read_b64_tr_b16 v[164:165], v183 offset:0
	ds_read_b64_tr_b16 v[166:167], v183 offset:2048
	ds_read_b64_tr_b16 v[168:169], v184 offset:0
	ds_read_b64_tr_b16 v[170:171], v184 offset:2048
	ds_read_b64_tr_b16 v[172:173], v185 offset:0
	ds_read_b64_tr_b16 v[174:175], v185 offset:2048
	s_mov_b64 exec, s[42:43]
	global_load_dwordx4 v[144:147], v189, s[40:41]
	global_load_dwordx4 v[148:151], v189, s[40:41] offset:64
	global_load_dwordx4 v[152:155], v189, s[40:41] offset:512
	global_load_dwordx4 v[156:159], v189, s[40:41] offset:576
	s_mov_b64 exec, -1
	s_mov_b32 m0, s49
	s_nop 0
	global_load_lds_dwordx4 v12, s[26:27]
	global_load_lds_dwordx4 v13, s[26:27] offset:1024
	global_load_lds_dwordx4 v14, s[26:27] offset:2048
	global_load_lds_dwordx4 v15, s[26:27] offset:3072
	s_waitcnt lgkmcnt(0)
	v_mfma_f32_16x16x32_bf16 v[128:131], v[160:163], v[96:99], 0
	v_mfma_f32_16x16x32_bf16 v[132:135], v[164:167], v[96:99], 0
	v_mfma_f32_16x16x32_bf16 v[136:139], v[168:171], v[96:99], 0
	v_mfma_f32_16x16x32_bf16 v[140:143], v[172:175], v[96:99], 0
	s_waitcnt vmcnt(12)
	ds_read_b64_tr_b16 v[160:161], v182 offset:4096
	ds_read_b64_tr_b16 v[162:163], v182 offset:6144
	ds_read_b64_tr_b16 v[164:165], v183 offset:4096
	ds_read_b64_tr_b16 v[166:167], v183 offset:6144
	ds_read_b64_tr_b16 v[168:169], v184 offset:4096
	ds_read_b64_tr_b16 v[170:171], v184 offset:6144
	ds_read_b64_tr_b16 v[172:173], v185 offset:4096
	ds_read_b64_tr_b16 v[174:175], v185 offset:6144
	s_mov_b32 m0, s46
	s_nop 0
	global_load_lds_dwordx4 v16, s[26:27]
	global_load_lds_dwordx4 v18, s[26:27] offset:1024
	global_load_lds_dwordx4 v19, s[26:27] offset:2048
	global_load_lds_dwordx4 v20, s[26:27] offset:3072
	s_waitcnt lgkmcnt(0)
	v_mfma_f32_16x16x32_bf16 v[128:131], v[160:163], v[100:103], v[128:131]
	v_mfma_f32_16x16x32_bf16 v[132:135], v[164:167], v[100:103], v[132:135]
	v_mfma_f32_16x16x32_bf16 v[136:139], v[168:171], v[100:103], v[136:139]
	v_mfma_f32_16x16x32_bf16 v[140:143], v[172:175], v[100:103], v[140:143]
	s_waitcnt vmcnt(12)
	ds_read_b64_tr_b16 v[160:161], v182 offset:8192
	ds_read_b64_tr_b16 v[162:163], v182 offset:10240
	ds_read_b64_tr_b16 v[164:165], v183 offset:8192
	ds_read_b64_tr_b16 v[166:167], v183 offset:10240
	ds_read_b64_tr_b16 v[168:169], v184 offset:8192
	ds_read_b64_tr_b16 v[170:171], v184 offset:10240
	ds_read_b64_tr_b16 v[172:173], v185 offset:8192
	ds_read_b64_tr_b16 v[174:175], v185 offset:10240
	s_mov_b32 m0, s47
	s_nop 0
	global_load_lds_dwordx4 v21, s[26:27]
	global_load_lds_dwordx4 v22, s[26:27] offset:1024
	global_load_lds_dwordx4 v23, s[26:27] offset:2048
	global_load_lds_dwordx4 v24, s[26:27] offset:3072
	s_waitcnt lgkmcnt(0)
	v_mfma_f32_16x16x32_bf16 v[128:131], v[160:163], v[104:107], v[128:131]
	v_mfma_f32_16x16x32_bf16 v[132:135], v[164:167], v[104:107], v[132:135]
	v_mfma_f32_16x16x32_bf16 v[136:139], v[168:171], v[104:107], v[136:139]
	v_mfma_f32_16x16x32_bf16 v[140:143], v[172:175], v[104:107], v[140:143]
	s_waitcnt vmcnt(8)
	ds_read_b64_tr_b16 v[160:161], v182 offset:12288
	ds_read_b64_tr_b16 v[162:163], v182 offset:14336
	ds_read_b64_tr_b16 v[164:165], v183 offset:12288
	ds_read_b64_tr_b16 v[166:167], v183 offset:14336
	ds_read_b64_tr_b16 v[168:169], v184 offset:12288
	ds_read_b64_tr_b16 v[170:171], v184 offset:14336
	ds_read_b64_tr_b16 v[172:173], v185 offset:12288
	ds_read_b64_tr_b16 v[174:175], v185 offset:14336
	s_mov_b32 m0, s48
	s_nop 0
	global_load_lds_dwordx4 v25, s[26:27]
	global_load_lds_dwordx4 v26, s[26:27] offset:1024
	global_load_lds_dwordx4 v27, s[26:27] offset:2048
	global_load_lds_dwordx4 v28, s[26:27] offset:3072
	s_waitcnt lgkmcnt(0)
; __device__ __forceinline__ void phase_attn(KP kp, int l, unsigned char* shm) {
;     ...
;     {
;       u32x2 sv = *(const u32x2*)(SEL + (size_t)r * 256 + lane * 4);
;       const int k0 = lane * 4;
;       unsigned a0 = sv[0] & 0xffffu, a1 = sv[0] >> 16, a2 = sv[1] & 0xffffu, a3 = sv[1] >> 16;
;       a0 = (k0 < cnt) ? a0 : 0u; a1 = (k0 + 1 < cnt) ? a1 : 0u; a2 = (k0 + 2 < cnt) ? a2 : 0u; a3 = (k0 + 3 < cnt) ? a3 : 0u;
;       u32x2 o;
;       o[0] = a0 | (a1 << 16); o[1] = a2 | (a3 << 16);
;       *(u32x2*)(selw + lane * 4) = o;
;     }
;     ...
;         for (int s8 = 0; s8 < 8; ++s8) {
; #pragma unroll
;           for (int it = 0; it < 4; ++it) *(u32x4*)(tileb + (it * 8 + ks8) * 144 + dc * 16) = vr[s8 * 4 + it];
;           u32x2 t0, t1, t2, t3, t4, t5, t6, t7;
;           asm volatile(
;               "ds_read_b64_tr_b16 %0, %8\n\tds_read_b64_tr_b16 %1, %8 offset:2304\n\t"
;               "ds_read_b64_tr_b16 %2, %8 offset:32\n\tds_read_b64_tr_b16 %3, %8 offset:2336\n\t"
;               "ds_read_b64_tr_b16 %4, %8 offset:64\n\tds_read_b64_tr_b16 %5, %8 offset:2368\n\t"
;               "ds_read_b64_tr_b16 %6, %8 offset:96\n\tds_read_b64_tr_b16 %7, %8 offset:2400\n\t"
;               "s_waitcnt lgkmcnt(0)"
;               : "=&v"(t0), "=&v"(t1), "=&v"(t2), "=&v"(t3), "=&v"(t4), "=&v"(t5), "=&v"(t6), "=&v"(t7)
;               : "v"(tr_addr)
;               : "memory");
;           const bf16x8 a0 = __builtin_bit_cast(bf16x8, (u32x4){t0[0], t0[1], t1[0], t1[1]});
;           const bf16x8 a1 = __builtin_bit_cast(bf16x8, (u32x4){t2[0], t2[1], t3[0], t3[1]});
;           const bf16x8 a2 = __builtin_bit_cast(bf16x8, (u32x4){t4[0], t4[1], t5[0], t5[1]});
;           const bf16x8 a3 = __builtin_bit_cast(bf16x8, (u32x4){t6[0], t6[1], t7[0], t7[1]});
;           oacc[0] = __builtin_amdgcn_mfma_f32_16x16x32_bf16(a0, pf[s8], oacc[0], 0, 0, 0);
;           oacc[1] = __builtin_amdgcn_mfma_f32_16x16x32_bf16(a1, pf[s8], oacc[1], 0, 0, 0);
;           oacc[2] = __builtin_amdgcn_mfma_f32_16x16x32_bf16(a2, pf[s8], oacc[2], 0, 0, 0);
;           oacc[3] = __builtin_amdgcn_mfma_f32_16x16x32_bf16(a3, pf[s8], oacc[3], 0, 0, 0);
	v_mfma_f32_16x16x32_bf16 v[128:131], v[160:163], v[108:111], v[128:131]
	v_mfma_f32_16x16x32_bf16 v[132:135], v[164:167], v[108:111], v[132:135]
	v_mfma_f32_16x16x32_bf16 v[136:139], v[168:171], v[108:111], v[136:139]
	v_mfma_f32_16x16x32_bf16 v[140:143], v[172:175], v[108:111], v[140:143]
	s_waitcnt vmcnt(8)
	ds_read_b64_tr_b16 v[160:161], v182 offset:0
	ds_read_b64_tr_b16 v[162:163], v182 offset:2048
	ds_read_b64_tr_b16 v[164:165], v183 offset:0
	ds_read_b64_tr_b16 v[166:167], v183 offset:2048
	ds_read_b64_tr_b16 v[168:169], v184 offset:0
	ds_read_b64_tr_b16 v[170:171], v184 offset:2048
	ds_read_b64_tr_b16 v[172:173], v185 offset:0
	ds_read_b64_tr_b16 v[174:175], v185 offset:2048
	s_mov_b32 m0, s49
	s_nop 0
	global_load_lds_dwordx4 v29, s[26:27]
	global_load_lds_dwordx4 v30, s[26:27] offset:1024
	global_load_lds_dwordx4 v31, s[26:27] offset:2048
	global_load_lds_dwordx4 v219, s[26:27] offset:3072
	s_waitcnt lgkmcnt(0)
	v_mfma_f32_16x16x32_bf16 v[128:131], v[160:163], v[112:115], v[128:131]
	v_mfma_f32_16x16x32_bf16 v[132:135], v[164:167], v[112:115], v[132:135]
	v_mfma_f32_16x16x32_bf16 v[136:139], v[168:171], v[112:115], v[136:139]
	v_mfma_f32_16x16x32_bf16 v[140:143], v[172:175], v[112:115], v[140:143]
	s_lshr_b32 s6, s45, 2
	v_cmp_gt_u32_e32 vcc, s6, v252
	s_nop 1
	v_cndmask_b32_e32 v198, 0, v198, vcc
	v_cndmask_b32_e32 v199, 0, v199, vcc
	ds_write_b64 v186, v[198:199]
	ds_read_u16 v0, v187 offset:0
	ds_read_u16 v1, v187 offset:16
	ds_read_u16 v2, v187 offset:32
	ds_read_u16 v3, v187 offset:48
	ds_read_u16 v4, v187 offset:64
	ds_read_u16 v5, v187 offset:80
	ds_read_u16 v6, v187 offset:96
	ds_read_u16 v7, v187 offset:112
	s_waitcnt lgkmcnt(0)
	v_lshl_add_u32 v0, v0, 8, v193
	v_lshl_add_u32 v1, v1, 8, v194
	v_lshl_add_u32 v2, v2, 8, v195
	v_lshl_add_u32 v3, v3, 8, v196
	v_lshl_add_u32 v4, v4, 8, v193
	v_lshl_add_u32 v5, v5, 8, v194
	v_lshl_add_u32 v6, v6, 8, v195
	v_lshl_add_u32 v7, v7, 8, v196
	ds_read_u16 v8, v187 offset:128
	ds_read_u16 v9, v187 offset:144
	ds_read_u16 v10, v187 offset:160
	ds_read_u16 v11, v187 offset:176
	ds_read_u16 v12, v187 offset:192
	ds_read_u16 v13, v187 offset:208
	ds_read_u16 v14, v187 offset:224
	ds_read_u16 v15, v187 offset:240
	s_waitcnt lgkmcnt(0)
	v_lshl_add_u32 v8, v8, 8, v193
	v_lshl_add_u32 v9, v9, 8, v194
	v_lshl_add_u32 v10, v10, 8, v195
	v_lshl_add_u32 v11, v11, 8, v196
	v_lshl_add_u32 v12, v12, 8, v193
	v_lshl_add_u32 v13, v13, 8, v194
	v_lshl_add_u32 v14, v14, 8, v195
	v_lshl_add_u32 v15, v15, 8, v196
	ds_read_u16 v16, v187 offset:256
	ds_read_u16 v18, v187 offset:272
	ds_read_u16 v19, v187 offset:288
	ds_read_u16 v20, v187 offset:304
	ds_read_u16 v21, v187 offset:320
	ds_read_u16 v22, v187 offset:336
	ds_read_u16 v23, v187 offset:352
	ds_read_u16 v24, v187 offset:368
	s_waitcnt lgkmcnt(0)
	v_lshl_add_u32 v16, v16, 8, v193
	v_lshl_add_u32 v18, v18, 8, v194
	v_lshl_add_u32 v19, v19, 8, v195
	v_lshl_add_u32 v20, v20, 8, v196
	v_lshl_add_u32 v21, v21, 8, v193
	v_lshl_add_u32 v22, v22, 8, v194
	v_lshl_add_u32 v23, v23, 8, v195
	v_lshl_add_u32 v24, v24, 8, v196
	ds_read_u16 v25, v187 offset:384
	ds_read_u16 v26, v187 offset:400
	ds_read_u16 v27, v187 offset:416
	ds_read_u16 v28, v187 offset:432
	ds_read_u16 v29, v187 offset:448
	ds_read_u16 v30, v187 offset:464
	ds_read_u16 v31, v187 offset:480
	ds_read_u16 v219, v187 offset:496
	s_waitcnt lgkmcnt(0)
	v_lshl_add_u32 v25, v25, 8, v193
	v_lshl_add_u32 v26, v26, 8, v194
	v_lshl_add_u32 v27, v27, 8, v195
	v_lshl_add_u32 v28, v28, 8, v196
	v_lshl_add_u32 v29, v29, 8, v193
	v_lshl_add_u32 v30, v30, 8, v194
	v_lshl_add_u32 v31, v31, 8, v195
	v_lshl_add_u32 v219, v219, 8, v196
	s_waitcnt vmcnt(8)
; __device__ __forceinline__ void phase_attn(KP kp, int l, unsigned char* shm) {
;     ...
;         for (int s8 = 0; s8 < 8; ++s8) {
; #pragma unroll
;           for (int it = 0; it < 4; ++it) *(u32x4*)(tileb + (it * 8 + ks8) * 144 + dc * 16) = vr[s8 * 4 + it];
;           u32x2 t0, t1, t2, t3, t4, t5, t6, t7;
;           asm volatile(
;               "ds_read_b64_tr_b16 %0, %8\n\tds_read_b64_tr_b16 %1, %8 offset:2304\n\t"
;               "ds_read_b64_tr_b16 %2, %8 offset:32\n\tds_read_b64_tr_b16 %3, %8 offset:2336\n\t"
;               "ds_read_b64_tr_b16 %4, %8 offset:64\n\tds_read_b64_tr_b16 %5, %8 offset:2368\n\t"
;               "ds_read_b64_tr_b16 %6, %8 offset:96\n\tds_read_b64_tr_b16 %7, %8 offset:2400\n\t"
;               "s_waitcnt lgkmcnt(0)"
;               : "=&v"(t0), "=&v"(t1), "=&v"(t2), "=&v"(t3), "=&v"(t4), "=&v"(t5), "=&v"(t6), "=&v"(t7)
;               : "v"(tr_addr)
;               : "memory");
;           const bf16x8 a0 = __builtin_bit_cast(bf16x8, (u32x4){t0[0], t0[1], t1[0], t1[1]});
;           const bf16x8 a1 = __builtin_bit_cast(bf16x8, (u32x4){t2[0], t2[1], t3[0], t3[1]});
;           const bf16x8 a2 = __builtin_bit_cast(bf16x8, (u32x4){t4[0], t4[1], t5[0], t5[1]});
;           const bf16x8 a3 = __builtin_bit_cast(bf16x8, (u32x4){t6[0], t6[1], t7[0], t7[1]});
;           oacc[0] = __builtin_amdgcn_mfma_f32_16x16x32_bf16(a0, pf[s8], oacc[0], 0, 0, 0);
;           oacc[1] = __builtin_amdgcn_mfma_f32_16x16x32_bf16(a1, pf[s8], oacc[1], 0, 0, 0);
;           oacc[2] = __builtin_amdgcn_mfma_f32_16x16x32_bf16(a2, pf[s8], oacc[2], 0, 0, 0);
;           oacc[3] = __builtin_amdgcn_mfma_f32_16x16x32_bf16(a3, pf[s8], oacc[3], 0, 0, 0);
;           if (kvh == 0 && s8 == 3) {
; #pragma unroll
;             for (int k8 = 0; k8 < 8; ++k8) {
;               const int idx = selw[k8 * 16 + nn];
;               const bf16_t* kp = kbase + (size_t)idx * 128 + 64 + kg * 8;
;               kpre[k8][0] = *(const bf16x8*)kp;
;               kpre[k8][1] = *(const bf16x8*)(kp + 32);
;             }
;           }
;         }
;         __builtin_amdgcn_sched_barrier(0);
;       }
;       if (nn < 4) {
; #pragma unroll
;         for (int c = 0; c < 4; ++c) {
;           u32x2 ow;
;           ow[0] = cvt_pk_bf16(oacc[c][0] * inv, oacc[c][1] * inv);
;           ow[1] = cvt_pk_bf16(oacc[c][2] * inv, oacc[c][3] * inv);
	ds_read_b64_tr_b16 v[160:161], v182 offset:4096
	ds_read_b64_tr_b16 v[162:163], v182 offset:6144
	ds_read_b64_tr_b16 v[164:165], v183 offset:4096
	ds_read_b64_tr_b16 v[166:167], v183 offset:6144
	ds_read_b64_tr_b16 v[168:169], v184 offset:4096
	ds_read_b64_tr_b16 v[170:171], v184 offset:6144
	ds_read_b64_tr_b16 v[172:173], v185 offset:4096
	ds_read_b64_tr_b16 v[174:175], v185 offset:6144
	s_mov_b32 m0, s46
	s_nop 0
	global_load_lds_dwordx4 v0, s[28:29]
	global_load_lds_dwordx4 v1, s[28:29] offset:1024
	global_load_lds_dwordx4 v2, s[28:29] offset:2048
	global_load_lds_dwordx4 v3, s[28:29] offset:3072
	s_waitcnt lgkmcnt(0)
	v_mfma_f32_16x16x32_bf16 v[128:131], v[160:163], v[116:119], v[128:131]
	v_mfma_f32_16x16x32_bf16 v[132:135], v[164:167], v[116:119], v[132:135]
	v_mfma_f32_16x16x32_bf16 v[136:139], v[168:171], v[116:119], v[136:139]
	v_mfma_f32_16x16x32_bf16 v[140:143], v[172:175], v[116:119], v[140:143]
	s_waitcnt vmcnt(8)
	ds_read_b64_tr_b16 v[160:161], v182 offset:8192
	ds_read_b64_tr_b16 v[162:163], v182 offset:10240
	ds_read_b64_tr_b16 v[164:165], v183 offset:8192
	ds_read_b64_tr_b16 v[166:167], v183 offset:10240
	ds_read_b64_tr_b16 v[168:169], v184 offset:8192
	ds_read_b64_tr_b16 v[170:171], v184 offset:10240
	ds_read_b64_tr_b16 v[172:173], v185 offset:8192
	ds_read_b64_tr_b16 v[174:175], v185 offset:10240
	s_mov_b32 m0, s47
	s_nop 0
	global_load_lds_dwordx4 v4, s[28:29]
	global_load_lds_dwordx4 v5, s[28:29] offset:1024
	global_load_lds_dwordx4 v6, s[28:29] offset:2048
	global_load_lds_dwordx4 v7, s[28:29] offset:3072
	s_waitcnt lgkmcnt(0)
	v_mfma_f32_16x16x32_bf16 v[128:131], v[160:163], v[120:123], v[128:131]
	v_mfma_f32_16x16x32_bf16 v[132:135], v[164:167], v[120:123], v[132:135]
	v_mfma_f32_16x16x32_bf16 v[136:139], v[168:171], v[120:123], v[136:139]
	v_mfma_f32_16x16x32_bf16 v[140:143], v[172:175], v[120:123], v[140:143]
	s_waitcnt vmcnt(8)
	ds_read_b64_tr_b16 v[160:161], v182 offset:12288
	ds_read_b64_tr_b16 v[162:163], v182 offset:14336
	ds_read_b64_tr_b16 v[164:165], v183 offset:12288
	ds_read_b64_tr_b16 v[166:167], v183 offset:14336
	ds_read_b64_tr_b16 v[168:169], v184 offset:12288
	ds_read_b64_tr_b16 v[170:171], v184 offset:14336
	ds_read_b64_tr_b16 v[172:173], v185 offset:12288
	ds_read_b64_tr_b16 v[174:175], v185 offset:14336
	s_mov_b32 m0, s48
	s_nop 0
	global_load_lds_dwordx4 v8, s[28:29]
	global_load_lds_dwordx4 v9, s[28:29] offset:1024
	global_load_lds_dwordx4 v10, s[28:29] offset:2048
	global_load_lds_dwordx4 v11, s[28:29] offset:3072
	s_waitcnt lgkmcnt(0)
	v_mfma_f32_16x16x32_bf16 v[128:131], v[160:163], v[124:127], v[128:131]
	v_mfma_f32_16x16x32_bf16 v[132:135], v[164:167], v[124:127], v[132:135]
	v_mfma_f32_16x16x32_bf16 v[136:139], v[168:171], v[124:127], v[136:139]
	v_mfma_f32_16x16x32_bf16 v[140:143], v[172:175], v[124:127], v[140:143]
	s_nop 7
	s_nop 3
	v_mul_f32_e32 v128, v208, v128
	v_mul_f32_e32 v129, v208, v129
	v_mul_f32_e32 v130, v208, v130
	v_mul_f32_e32 v131, v208, v131
	v_cvt_pk_bf16_f32 v200, v128, v129
	v_cvt_pk_bf16_f32 v201, v130, v131
	v_mul_f32_e32 v132, v208, v132
	v_mul_f32_e32 v133, v208, v133
	v_mul_f32_e32 v134, v208, v134
	v_mul_f32_e32 v135, v208, v135
	v_cvt_pk_bf16_f32 v202, v132, v133
	v_cvt_pk_bf16_f32 v203, v134, v135
	v_mul_f32_e32 v136, v208, v136
	v_mul_f32_e32 v137, v208, v137
	v_mul_f32_e32 v138, v208, v138
	v_mul_f32_e32 v139, v208, v139
	v_cvt_pk_bf16_f32 v204, v136, v137
	v_cvt_pk_bf16_f32 v205, v138, v139
	v_mul_f32_e32 v140, v208, v140
	v_mul_f32_e32 v141, v208, v141
	v_mul_f32_e32 v142, v208, v142
	v_mul_f32_e32 v143, v208, v143
	v_cvt_pk_bf16_f32 v206, v140, v141
	v_cvt_pk_bf16_f32 v207, v142, v143
	s_mov_b64 exec, s[42:43]
	global_store_dwordx2 v190, v[200:201], s[34:35] offset:512
	global_store_dwordx2 v190, v[202:203], s[34:35] offset:544
	global_store_dwordx2 v190, v[204:205], s[34:35] offset:576
	global_store_dwordx2 v190, v[206:207], s[34:35] offset:608
	s_mov_b64 exec, -1
	s_mov_b64 s[20:21], s[28:29]
	s_mov_b64 s[22:23], s[30:31]
	s_add_u32 s24, s28, 0x80
	s_addc_u32 s25, s29, 0
	s_add_u32 s26, s30, 0x80
	s_addc_u32 s27, s31, 0
	s_mov_b64 s[34:35], s[36:37]
	s_mov_b32 s44, s45
	s_mov_b32 s2, s50
	s_cmp_lt_i32 s2, 0x8200
	s_cbranch_scc1 .Lattn_loop
